# v27 + sample-token HGRN2 unit wave sum via DPP / permlane16-32 swaps + gate/up sample-row epilogue lane fetches via DPP row_shr (no ds_bpermute round trips)
# baseline (speedup 1.0000x reference)
; __device__ __forceinline__ float ex2(float x) { return __builtin_amdgcn_exp2f(x); }
; __device__ __forceinline__ void hgrn_sample_unit(int unit, LAS unsigned char* lds, const float* sh, const float* HLF, const bf16* HQ, const bf16* HV, const bf16* HG, bf16* MIX, float* ohs, gu32* rdy4) {
;     ...
;     const float* s0 = sh + ((size_t)unit * 128 + 8 * kq) * 128 + 4 * v4;
;     f32x4 S[8];
; #pragma unroll
;     for (int i = 0; i < 8; ++i) S[i] = *(const f32x4*)(s0 + i * 128);
; #pragma unroll
;     for (int t = 0; t < 4; ++t) {
;         const size_t rb = (size_t)(MP + 4 * b + t) * 512 + h * 128;
;         const v2u vw = *(const v2u*)(HV + rb + 4 * v4);
;         const f32x4 vv = {__builtin_bit_cast(float, vw.x << 16), __builtin_bit_cast(float, vw.x & 0xffff0000u), __builtin_bit_cast(float, vw.y << 16), __builtin_bit_cast(float, vw.y & 0xffff0000u)};
;         f32x4 po = {0.f, 0.f, 0.f, 0.f};
; #pragma unroll
;         for (int i = 0; i < 8; ++i) { const float f = ex2(HLF[rb + 8 * kq + i] * LOG2E_F), q = bf2f(HQ[rb + 8 * kq + i]); S[i] = S[i] * f + vv * (1.0f - f); po += S[i] * q; }
.LBB0_602:
	s_and_b32 s22, s26, -4
	s_ashr_i32 s23, s22, 31
	s_and_b32 s12, s0, 0x180
	s_lshl_b64 s[24:25], s[22:23], 9
	s_or_b32 s23, s24, s12
	s_add_u32 s28, s23, 0x800000
	s_addc_u32 s29, s25, 0
	v_lshl_add_u64 v[2:3], s[28:29], 1, v[26:27]
	global_load_dwordx2 v[48:49], v[2:3], off
	v_mov_b32_e32 v3, s29
	v_or_b32_e32 v2, s28, v22
	v_lshl_add_u64 v[4:5], v[2:3], 2, s[14:15]
	global_load_dwordx4 v[10:13], v[4:5], off
	v_lshl_add_u64 v[2:3], v[2:3], 1, s[16:17]
	global_load_dwordx4 v[14:17], v[2:3], off
	global_load_dwordx4 v[52:55], v[4:5], off offset:16
	v_lshl_add_u64 v[2:3], v[30:31], 0, v[28:29]
	global_load_dwordx4 v[56:59], v[2:3], off
	global_load_dwordx4 v[60:63], v[2:3], off offset:512
	global_load_dwordx4 v[68:71], v[2:3], off offset:1024
	global_load_dwordx4 v[72:75], v[2:3], off offset:1536
	global_load_dwordx4 v[76:79], v[2:3], off offset:2048
	global_load_dwordx4 v[80:83], v[2:3], off offset:2560
	global_load_dwordx4 v[84:87], v[2:3], off offset:3072
	global_load_dwordx4 v[88:91], v[2:3], off offset:3584
	s_add_u32 s28, s23, 0x800200
	s_addc_u32 s29, s25, 0
	v_or_b32_e32 v2, s28, v22
	v_lshl_add_u64 v[64:65], s[28:29], 1, v[26:27]
	v_mov_b32_e32 v3, s29
	v_lshl_add_u64 v[92:93], v[2:3], 2, s[14:15]
	v_lshl_add_u64 v[94:95], v[2:3], 1, s[16:17]
	global_load_dwordx2 v[96:97], v[64:65], off
	global_load_dwordx4 v[18:21], v[92:93], off
	global_load_dwordx4 v[6:9], v[92:93], off offset:16
	global_load_dwordx4 v[2:5], v[94:95], off
	s_add_u32 s28, s23, 0x800400
	s_addc_u32 s29, s25, 0
	s_add_u32 s24, s23, 0x800600
	s_addc_u32 s25, s25, 0
	v_lshl_add_u64 v[216:217], s[28:29], 1, v[26:27]
	global_load_dwordx2 v[200:201], v[216:217], off
	v_mov_b32_e32 v219, s29
	v_or_b32_e32 v218, s28, v22
	v_lshl_add_u64 v[220:221], v[218:219], 2, s[14:15]
	v_lshl_add_u64 v[222:223], v[218:219], 1, s[16:17]
	global_load_dwordx4 v[204:207], v[220:221], off
	global_load_dwordx4 v[208:211], v[220:221], off offset:16
	global_load_dwordx4 v[212:215], v[222:223], off
	v_lshl_add_u64 v[216:217], s[24:25], 1, v[26:27]
	global_load_dwordx2 v[224:225], v[216:217], off
	v_mov_b32_e32 v219, s25
	v_or_b32_e32 v218, s24, v22
	v_lshl_add_u64 v[220:221], v[218:219], 2, s[14:15]
	v_lshl_add_u64 v[222:223], v[218:219], 1, s[16:17]
	global_load_dwordx4 v[232:235], v[220:221], off
	global_load_dwordx4 v[236:239], v[220:221], off offset:16
	global_load_dwordx4 v[240:243], v[222:223], off
	v_cmp_lt_i32_e32 vcc, v39, v38
	s_waitcnt vmcnt(23)
	v_lshlrev_b32_e32 v64, 16, v48
	v_and_b32_e32 v65, 0xffff0000, v48
	v_lshlrev_b32_e32 v48, 16, v49
	v_and_b32_e32 v49, 0xffff0000, v49
	s_waitcnt vmcnt(22)
	v_mul_f32_e32 v51, 0x3fb8aa3b, v10
	v_mul_f32_e32 v11, 0x3fb8aa3b, v11
	s_waitcnt vmcnt(20)
	v_mul_f32_e32 v93, 0x3fb8aa3b, v54
	v_exp_f32_e32 v54, v51
	v_mul_f32_e32 v67, 0x3fb8aa3b, v12
	v_exp_f32_e32 v94, v11
	v_mul_f32_e32 v13, 0x3fb8aa3b, v13
	v_exp_f32_e32 v98, v67
	v_lshlrev_b32_e32 v12, 16, v15
	v_and_b32_e32 v92, 0xffff0000, v15
	v_mul_f32_e32 v15, 0x3fb8aa3b, v52
	v_exp_f32_e32 v100, v13
	v_mul_f32_e32 v53, 0x3fb8aa3b, v53
	v_exp_f32_e32 v102, v15
	v_sub_f32_e32 v108, 1.0, v54
	v_exp_f32_e32 v104, v53
	v_sub_f32_e32 v110, 1.0, v94
	v_pk_mul_f32 v[120:121], v[108:109], v[64:65] op_sel_hi:[0,1]
	v_pk_mul_f32 v[108:109], v[108:109], v[48:49] op_sel_hi:[0,1]
	v_lshlrev_b32_e32 v10, 16, v14
	v_sub_f32_e32 v112, 1.0, v98
	v_pk_mul_f32 v[122:123], v[110:111], v[48:49] op_sel_hi:[0,1]
	v_pk_mul_f32 v[110:111], v[110:111], v[64:65] op_sel_hi:[0,1]
	s_waitcnt vmcnt(19)
	v_pk_fma_f32 v[58:59], v[58:59], v[54:55], v[108:109] op_sel_hi:[1,0,1]
	v_pk_fma_f32 v[56:57], v[56:57], v[54:55], v[120:121] op_sel_hi:[1,0,1]
	v_and_b32_e32 v14, 0xffff0000, v14
	v_sub_f32_e32 v114, 1.0, v100
	v_pk_mul_f32 v[124:125], v[112:113], v[64:65] op_sel_hi:[0,1]
	v_pk_mul_f32 v[112:113], v[112:113], v[48:49] op_sel_hi:[0,1]
	s_waitcnt vmcnt(18)
	v_pk_fma_f32 v[60:61], v[60:61], v[94:95], v[110:111] op_sel_hi:[1,0,1]
	v_pk_fma_f32 v[62:63], v[62:63], v[94:95], v[122:123] op_sel_hi:[1,0,1]
	v_pk_fma_f32 v[94:95], v[10:11], v[56:57], 0 op_sel_hi:[0,1,0]
	v_pk_fma_f32 v[10:11], v[10:11], v[58:59], 0 op_sel_hi:[0,1,0]
	v_exp_f32_e32 v106, v93
	v_sub_f32_e32 v116, 1.0, v102
	v_pk_mul_f32 v[126:127], v[114:115], v[48:49] op_sel_hi:[0,1]
	v_pk_mul_f32 v[114:115], v[114:115], v[64:65] op_sel_hi:[0,1]
	s_waitcnt vmcnt(17)
	v_pk_fma_f32 v[70:71], v[70:71], v[98:99], v[112:113] op_sel_hi:[1,0,1]
	v_pk_fma_f32 v[68:69], v[68:69], v[98:99], v[124:125] op_sel_hi:[1,0,1]
	v_pk_fma_f32 v[10:11], v[14:15], v[62:63], v[10:11] op_sel_hi:[0,1,1]
	v_pk_fma_f32 v[14:15], v[14:15], v[60:61], v[94:95] op_sel_hi:[0,1,1]
	v_sub_f32_e32 v118, 1.0, v104
	v_pk_mul_f32 v[128:129], v[116:117], v[64:65] op_sel_hi:[0,1]
	v_pk_mul_f32 v[116:117], v[116:117], v[48:49] op_sel_hi:[0,1]
	s_waitcnt vmcnt(16)
	v_pk_fma_f32 v[72:73], v[72:73], v[100:101], v[114:115] op_sel_hi:[1,0,1]
	v_pk_fma_f32 v[74:75], v[74:75], v[100:101], v[126:127] op_sel_hi:[1,0,1]
	v_pk_fma_f32 v[14:15], v[12:13], v[68:69], v[14:15] op_sel_hi:[0,1,1]
	v_pk_fma_f32 v[10:11], v[12:13], v[70:71], v[10:11] op_sel_hi:[0,1,1]
	v_lshlrev_b32_e32 v52, 16, v16
	v_pk_mul_f32 v[130:131], v[118:119], v[48:49] op_sel_hi:[0,1]
	v_pk_mul_f32 v[118:119], v[118:119], v[64:65] op_sel_hi:[0,1]
	s_waitcnt vmcnt(15)
	v_pk_fma_f32 v[78:79], v[78:79], v[102:103], v[116:117] op_sel_hi:[1,0,1]
	v_pk_fma_f32 v[76:77], v[76:77], v[102:103], v[128:129] op_sel_hi:[1,0,1]
	v_pk_fma_f32 v[10:11], v[92:93], v[74:75], v[10:11] op_sel_hi:[0,1,1]
	v_pk_fma_f32 v[12:13], v[92:93], v[72:73], v[14:15] op_sel_hi:[0,1,1]
	v_and_b32_e32 v16, 0xffff0000, v16
	s_waitcnt vmcnt(14)
; #define LAS __attribute__((address_space(3)))
; __device__ __forceinline__ float ex2(float x) { return __builtin_amdgcn_exp2f(x); }
; __device__ __forceinline__ void hgrn_sample_unit(int unit, LAS unsigned char* lds, const float* sh, const float* HLF, const bf16* HQ, const bf16* HV, const bf16* HG, bf16* MIX, float* ohs, gu32* rdy4) {
;     ...
;     for (int t = 0; t < 4; ++t) {
;         const size_t rb = (size_t)(MP + 4 * b + t) * 512 + h * 128;
;         const v2u vw = *(const v2u*)(HV + rb + 4 * v4);
;         const f32x4 vv = {__builtin_bit_cast(float, vw.x << 16), __builtin_bit_cast(float, vw.x & 0xffff0000u), __builtin_bit_cast(float, vw.y << 16), __builtin_bit_cast(float, vw.y & 0xffff0000u)};
;         f32x4 po = {0.f, 0.f, 0.f, 0.f};
; #pragma unroll
;         for (int i = 0; i < 8; ++i) { const float f = ex2(HLF[rb + 8 * kq + i] * LOG2E_F), q = bf2f(HQ[rb + 8 * kq + i]); S[i] = S[i] * f + vv * (1.0f - f); po += S[i] * q; }
;         *(LAS f32x4*)(OP + (t * 16 + kq) * 128 + 4 * v4) = po;
	v_pk_fma_f32 v[80:81], v[80:81], v[104:105], v[118:119] op_sel_hi:[1,0,1]
	v_pk_fma_f32 v[82:83], v[82:83], v[104:105], v[130:131] op_sel_hi:[1,0,1]
	v_pk_fma_f32 v[12:13], v[52:53], v[76:77], v[12:13] op_sel_hi:[0,1,1]
	v_pk_fma_f32 v[10:11], v[52:53], v[78:79], v[10:11] op_sel_hi:[0,1,1]
	v_pk_fma_f32 v[10:11], v[16:17], v[82:83], v[10:11] op_sel_hi:[0,1,1]
	v_pk_fma_f32 v[12:13], v[16:17], v[80:81], v[12:13] op_sel_hi:[0,1,1]
	v_sub_f32_e32 v16, 1.0, v106
	v_mul_f32_e32 v15, 0x3fb8aa3b, v55
	v_pk_mul_f32 v[52:53], v[16:17], v[64:65] op_sel_hi:[0,1]
	v_pk_mul_f32 v[92:93], v[16:17], v[48:49] op_sel_hi:[0,1]
	v_exp_f32_e32 v16, v15
	v_lshlrev_b32_e32 v14, 16, v17
	s_waitcnt vmcnt(13)
	v_pk_fma_f32 v[84:85], v[84:85], v[106:107], v[52:53] op_sel_hi:[1,0,1]
	v_pk_fma_f32 v[86:87], v[86:87], v[106:107], v[92:93] op_sel_hi:[1,0,1]
	v_pk_fma_f32 v[52:53], v[14:15], v[84:85], v[12:13] op_sel_hi:[0,1,1]
	v_sub_f32_e32 v12, 1.0, v16
	v_pk_mul_f32 v[48:49], v[12:13], v[48:49] op_sel_hi:[0,1]
	v_pk_mul_f32 v[12:13], v[12:13], v[64:65] op_sel_hi:[0,1]
	v_pk_fma_f32 v[10:11], v[14:15], v[86:87], v[10:11] op_sel_hi:[0,1,1]
	v_and_b32_e32 v14, 0xffff0000, v17
	s_waitcnt vmcnt(12)
	v_pk_fma_f32 v[64:65], v[88:89], v[16:17], v[12:13] op_sel_hi:[1,0,1]
	v_pk_fma_f32 v[48:49], v[90:91], v[16:17], v[48:49] op_sel_hi:[1,0,1]
	s_waitcnt vmcnt(11)
	v_lshlrev_b32_e32 v88, 16, v96
	v_pk_fma_f32 v[12:13], v[14:15], v[48:49], v[10:11] op_sel_hi:[0,1,1]
	v_pk_fma_f32 v[10:11], v[14:15], v[64:65], v[52:53] op_sel_hi:[0,1,1]
	ds_write_b128 v1, v[10:13]
	s_waitcnt vmcnt(10)
	v_mul_f32_e32 v10, 0x3fb8aa3b, v18
	v_exp_f32_e32 v10, v10
	v_and_b32_e32 v89, 0xffff0000, v96
	v_lshlrev_b32_e32 v90, 16, v97
	v_and_b32_e32 v91, 0xffff0000, v97
	v_sub_f32_e32 v12, 1.0, v10
	v_pk_mul_f32 v[14:15], v[12:13], v[88:89] op_sel_hi:[0,1]
	v_pk_mul_f32 v[12:13], v[12:13], v[90:91] op_sel_hi:[0,1]
	v_pk_fma_f32 v[58:59], v[58:59], v[10:11], v[12:13] op_sel_hi:[1,0,1]
	v_mul_f32_e32 v19, 0x3fb8aa3b, v19
	v_pk_fma_f32 v[56:57], v[56:57], v[10:11], v[14:15] op_sel_hi:[1,0,1]
	v_exp_f32_e32 v94, v19
	v_mul_f32_e32 v20, 0x3fb8aa3b, v20
	v_exp_f32_e32 v20, v20
	s_waitcnt vmcnt(8)
	v_lshlrev_b32_e32 v18, 16, v2
	v_sub_f32_e32 v98, 1.0, v94
	v_pk_mul_f32 v[100:101], v[98:99], v[90:91] op_sel_hi:[0,1]
	v_pk_mul_f32 v[98:99], v[98:99], v[88:89] op_sel_hi:[0,1]
	v_pk_fma_f32 v[96:97], v[18:19], v[56:57], 0 op_sel_hi:[0,1,0]
	v_and_b32_e32 v2, 0xffff0000, v2
	v_pk_fma_f32 v[60:61], v[60:61], v[94:95], v[98:99] op_sel_hi:[1,0,1]
	v_pk_fma_f32 v[62:63], v[62:63], v[94:95], v[100:101] op_sel_hi:[1,0,1]
	v_pk_fma_f32 v[94:95], v[2:3], v[60:61], v[96:97] op_sel_hi:[0,1,1]
	v_sub_f32_e32 v96, 1.0, v20
	v_pk_mul_f32 v[98:99], v[96:97], v[88:89] op_sel_hi:[0,1]
	v_pk_mul_f32 v[96:97], v[96:97], v[90:91] op_sel_hi:[0,1]
	v_pk_fma_f32 v[70:71], v[70:71], v[20:21], v[96:97] op_sel_hi:[1,0,1]
	v_pk_fma_f32 v[68:69], v[68:69], v[20:21], v[98:99] op_sel_hi:[1,0,1]
	v_mul_f32_e32 v20, 0x3fb8aa3b, v21
	v_pk_fma_f32 v[18:19], v[18:19], v[58:59], 0 op_sel_hi:[0,1,0]
	v_exp_f32_e32 v20, v20
	v_pk_fma_f32 v[18:19], v[2:3], v[62:63], v[18:19] op_sel_hi:[0,1,1]
	v_lshlrev_b32_e32 v2, 16, v3
	v_pk_fma_f32 v[94:95], v[2:3], v[68:69], v[94:95] op_sel_hi:[0,1,1]
	v_pk_fma_f32 v[18:19], v[2:3], v[70:71], v[18:19] op_sel_hi:[0,1,1]
	v_and_b32_e32 v2, 0xffff0000, v3
	v_mul_f32_e32 v3, 0x3fb8aa3b, v6
	v_exp_f32_e32 v6, v3
	v_sub_f32_e32 v96, 1.0, v20
	v_pk_mul_f32 v[98:99], v[96:97], v[90:91] op_sel_hi:[0,1]
	v_pk_mul_f32 v[96:97], v[96:97], v[88:89] op_sel_hi:[0,1]
	v_pk_fma_f32 v[72:73], v[72:73], v[20:21], v[96:97] op_sel_hi:[1,0,1]
	v_pk_fma_f32 v[74:75], v[74:75], v[20:21], v[98:99] op_sel_hi:[1,0,1]
	v_lshlrev_b32_e32 v20, 16, v4
	v_pk_fma_f32 v[18:19], v[2:3], v[74:75], v[18:19] op_sel_hi:[0,1,1]
	v_pk_fma_f32 v[2:3], v[2:3], v[72:73], v[94:95] op_sel_hi:[0,1,1]
	v_sub_f32_e32 v94, 1.0, v6
	v_pk_mul_f32 v[96:97], v[94:95], v[88:89] op_sel_hi:[0,1]
	v_pk_mul_f32 v[94:95], v[94:95], v[90:91] op_sel_hi:[0,1]
	v_pk_fma_f32 v[78:79], v[78:79], v[6:7], v[94:95] op_sel_hi:[1,0,1]
	v_pk_fma_f32 v[76:77], v[76:77], v[6:7], v[96:97] op_sel_hi:[1,0,1]
	v_mul_f32_e32 v6, 0x3fb8aa3b, v7
	v_exp_f32_e32 v6, v6
	v_pk_fma_f32 v[2:3], v[20:21], v[76:77], v[2:3] op_sel_hi:[0,1,1]
	v_pk_fma_f32 v[18:19], v[20:21], v[78:79], v[18:19] op_sel_hi:[0,1,1]
	v_and_b32_e32 v4, 0xffff0000, v4
	v_sub_f32_e32 v20, 1.0, v6
	v_pk_mul_f32 v[94:95], v[20:21], v[90:91] op_sel_hi:[0,1]
	v_pk_mul_f32 v[20:21], v[20:21], v[88:89] op_sel_hi:[0,1]
	v_pk_fma_f32 v[80:81], v[80:81], v[6:7], v[20:21] op_sel_hi:[1,0,1]
	v_pk_fma_f32 v[82:83], v[82:83], v[6:7], v[94:95] op_sel_hi:[1,0,1]
	v_mul_f32_e32 v6, 0x3fb8aa3b, v8
	v_exp_f32_e32 v6, v6
	v_pk_fma_f32 v[18:19], v[4:5], v[82:83], v[18:19] op_sel_hi:[0,1,1]
	v_pk_fma_f32 v[2:3], v[4:5], v[80:81], v[2:3] op_sel_hi:[0,1,1]
	v_lshlrev_b32_e32 v4, 16, v5
	v_sub_f32_e32 v8, 1.0, v6
	v_pk_mul_f32 v[20:21], v[8:9], v[88:89] op_sel_hi:[0,1]
	v_pk_mul_f32 v[94:95], v[8:9], v[90:91] op_sel_hi:[0,1]
	v_pk_fma_f32 v[86:87], v[86:87], v[6:7], v[94:95] op_sel_hi:[1,0,1]
	v_pk_fma_f32 v[84:85], v[84:85], v[6:7], v[20:21] op_sel_hi:[1,0,1]
	v_mul_f32_e32 v6, 0x3fb8aa3b, v9
	v_exp_f32_e32 v6, v6
	v_pk_fma_f32 v[2:3], v[4:5], v[84:85], v[2:3] op_sel_hi:[0,1,1]
	v_pk_fma_f32 v[8:9], v[4:5], v[86:87], v[18:19] op_sel_hi:[0,1,1]
	v_and_b32_e32 v18, 0xffff0000, v5
	v_sub_f32_e32 v4, 1.0, v6
	v_pk_mul_f32 v[20:21], v[4:5], v[90:91] op_sel_hi:[0,1]
	v_pk_mul_f32 v[4:5], v[4:5], v[88:89] op_sel_hi:[0,1]
	v_pk_fma_f32 v[64:65], v[64:65], v[6:7], v[4:5] op_sel_hi:[1,0,1]
	v_pk_fma_f32 v[48:49], v[48:49], v[6:7], v[20:21] op_sel_hi:[1,0,1]
	v_pk_fma_f32 v[2:3], v[18:19], v[64:65], v[2:3] op_sel_hi:[0,1,1]
	v_pk_fma_f32 v[4:5], v[18:19], v[48:49], v[8:9] op_sel_hi:[0,1,1]
	ds_write_b128 v1, v[2:5] offset:8192
	s_waitcnt vmcnt(7)
; #define LAS __attribute__((address_space(3)))
; __device__ __forceinline__ float ex2(float x) { return __builtin_amdgcn_exp2f(x); }
; __device__ __forceinline__ void hgrn_sample_unit(int unit, LAS unsigned char* lds, const float* sh, const float* HLF, const bf16* HQ, const bf16* HV, const bf16* HG, bf16* MIX, float* ohs, gu32* rdy4) {
;     ...
;     for (int t = 0; t < 4; ++t) {
;         const size_t rb = (size_t)(MP + 4 * b + t) * 512 + h * 128;
;         const v2u vw = *(const v2u*)(HV + rb + 4 * v4);
;         const f32x4 vv = {__builtin_bit_cast(float, vw.x << 16), __builtin_bit_cast(float, vw.x & 0xffff0000u), __builtin_bit_cast(float, vw.y << 16), __builtin_bit_cast(float, vw.y & 0xffff0000u)};
;         f32x4 po = {0.f, 0.f, 0.f, 0.f};
; #pragma unroll
;         for (int i = 0; i < 8; ++i) { const float f = ex2(HLF[rb + 8 * kq + i] * LOG2E_F), q = bf2f(HQ[rb + 8 * kq + i]); S[i] = S[i] * f + vv * (1.0f - f); po += S[i] * q; }
;         *(LAS f32x4*)(OP + (t * 16 + kq) * 128 + 4 * v4) = po;
	v_lshlrev_b32_e32 v88, 16, v200
	v_and_b32_e32 v89, 0xffff0000, v200
	s_waitcnt vmcnt(6)
	v_mul_f32_e32 v2, 0x3fb8aa3b, v204
	v_exp_f32_e32 v6, v2
	v_lshlrev_b32_e32 v90, 16, v201
	v_and_b32_e32 v91, 0xffff0000, v201
	v_sub_f32_e32 v2, 1.0, v6
	v_pk_mul_f32 v[8:9], v[2:3], v[88:89] op_sel_hi:[0,1]
	v_pk_mul_f32 v[2:3], v[2:3], v[90:91] op_sel_hi:[0,1]
	v_pk_fma_f32 v[58:59], v[58:59], v[6:7], v[2:3] op_sel_hi:[1,0,1]
	v_pk_fma_f32 v[56:57], v[56:57], v[6:7], v[8:9] op_sel_hi:[1,0,1]
	v_mul_f32_e32 v51, 0x3fb8aa3b, v205
	v_exp_f32_e32 v94, v51
	v_mul_f32_e32 v51, 0x3fb8aa3b, v206
	v_exp_f32_e32 v54, v51
	s_waitcnt vmcnt(4)
	v_lshlrev_b32_e32 v52, 16, v212
	v_sub_f32_e32 v98, 1.0, v94
	v_pk_mul_f32 v[100:101], v[98:99], v[90:91] op_sel_hi:[0,1]
	v_pk_mul_f32 v[98:99], v[98:99], v[88:89] op_sel_hi:[0,1]
	v_pk_fma_f32 v[96:97], v[52:53], v[56:57], 0 op_sel_hi:[0,1,0]
	v_and_b32_e32 v10, 0xffff0000, v212
	v_pk_fma_f32 v[60:61], v[60:61], v[94:95], v[98:99] op_sel_hi:[1,0,1]
	v_pk_fma_f32 v[62:63], v[62:63], v[94:95], v[100:101] op_sel_hi:[1,0,1]
	v_pk_fma_f32 v[94:95], v[10:11], v[60:61], v[96:97] op_sel_hi:[0,1,1]
	v_sub_f32_e32 v96, 1.0, v54
	v_pk_mul_f32 v[98:99], v[96:97], v[88:89] op_sel_hi:[0,1]
	v_pk_mul_f32 v[96:97], v[96:97], v[90:91] op_sel_hi:[0,1]
	v_mul_f32_e32 v51, 0x3fb8aa3b, v207
	v_pk_fma_f32 v[52:53], v[52:53], v[58:59], 0 op_sel_hi:[0,1,0]
	v_pk_fma_f32 v[70:71], v[70:71], v[54:55], v[96:97] op_sel_hi:[1,0,1]
	v_pk_fma_f32 v[68:69], v[68:69], v[54:55], v[98:99] op_sel_hi:[1,0,1]
	v_exp_f32_e32 v54, v51
	v_pk_fma_f32 v[52:53], v[10:11], v[62:63], v[52:53] op_sel_hi:[0,1,1]
	v_lshlrev_b32_e32 v10, 16, v213
	v_pk_fma_f32 v[94:95], v[10:11], v[68:69], v[94:95] op_sel_hi:[0,1,1]
	v_pk_fma_f32 v[52:53], v[10:11], v[70:71], v[52:53] op_sel_hi:[0,1,1]
	v_and_b32_e32 v10, 0xffff0000, v213
	v_mul_f32_e32 v11, 0x3fb8aa3b, v208
	v_exp_f32_e32 v14, v11
	v_sub_f32_e32 v96, 1.0, v54
	v_pk_mul_f32 v[98:99], v[96:97], v[90:91] op_sel_hi:[0,1]
	v_pk_mul_f32 v[96:97], v[96:97], v[88:89] op_sel_hi:[0,1]
	v_pk_fma_f32 v[72:73], v[72:73], v[54:55], v[96:97] op_sel_hi:[1,0,1]
	v_pk_fma_f32 v[74:75], v[74:75], v[54:55], v[98:99] op_sel_hi:[1,0,1]
	v_lshlrev_b32_e32 v54, 16, v214
	v_pk_fma_f32 v[52:53], v[10:11], v[74:75], v[52:53] op_sel_hi:[0,1,1]
	v_pk_fma_f32 v[10:11], v[10:11], v[72:73], v[94:95] op_sel_hi:[0,1,1]
	v_sub_f32_e32 v94, 1.0, v14
	v_pk_mul_f32 v[96:97], v[94:95], v[88:89] op_sel_hi:[0,1]
	v_pk_mul_f32 v[94:95], v[94:95], v[90:91] op_sel_hi:[0,1]
	v_pk_fma_f32 v[78:79], v[78:79], v[14:15], v[94:95] op_sel_hi:[1,0,1]
	v_pk_fma_f32 v[76:77], v[76:77], v[14:15], v[96:97] op_sel_hi:[1,0,1]
	v_mul_f32_e32 v14, 0x3fb8aa3b, v209
	v_exp_f32_e32 v14, v14
	v_pk_fma_f32 v[10:11], v[54:55], v[76:77], v[10:11] op_sel_hi:[0,1,1]
	v_pk_fma_f32 v[52:53], v[54:55], v[78:79], v[52:53] op_sel_hi:[0,1,1]
	v_and_b32_e32 v12, 0xffff0000, v214
	v_sub_f32_e32 v54, 1.0, v14
	v_pk_mul_f32 v[94:95], v[54:55], v[90:91] op_sel_hi:[0,1]
	v_pk_mul_f32 v[54:55], v[54:55], v[88:89] op_sel_hi:[0,1]
	v_pk_fma_f32 v[80:81], v[80:81], v[14:15], v[54:55] op_sel_hi:[1,0,1]
	v_pk_fma_f32 v[82:83], v[82:83], v[14:15], v[94:95] op_sel_hi:[1,0,1]
	v_mul_f32_e32 v14, 0x3fb8aa3b, v210
	v_exp_f32_e32 v14, v14
	v_pk_fma_f32 v[52:53], v[12:13], v[82:83], v[52:53] op_sel_hi:[0,1,1]
	v_pk_fma_f32 v[10:11], v[12:13], v[80:81], v[10:11] op_sel_hi:[0,1,1]
	v_lshlrev_b32_e32 v12, 16, v215
	v_sub_f32_e32 v16, 1.0, v14
	v_pk_mul_f32 v[54:55], v[16:17], v[88:89] op_sel_hi:[0,1]
	v_pk_mul_f32 v[94:95], v[16:17], v[90:91] op_sel_hi:[0,1]
	v_pk_fma_f32 v[86:87], v[86:87], v[14:15], v[94:95] op_sel_hi:[1,0,1]
	v_pk_fma_f32 v[84:85], v[84:85], v[14:15], v[54:55] op_sel_hi:[1,0,1]
	v_mul_f32_e32 v14, 0x3fb8aa3b, v211
	v_exp_f32_e32 v14, v14
	v_pk_fma_f32 v[10:11], v[12:13], v[84:85], v[10:11] op_sel_hi:[0,1,1]
	v_pk_fma_f32 v[16:17], v[12:13], v[86:87], v[52:53] op_sel_hi:[0,1,1]
	v_and_b32_e32 v52, 0xffff0000, v215
	v_sub_f32_e32 v12, 1.0, v14
	v_pk_mul_f32 v[54:55], v[12:13], v[90:91] op_sel_hi:[0,1]
	v_pk_mul_f32 v[12:13], v[12:13], v[88:89] op_sel_hi:[0,1]
	v_pk_fma_f32 v[64:65], v[64:65], v[14:15], v[12:13] op_sel_hi:[1,0,1]
	v_pk_fma_f32 v[48:49], v[48:49], v[14:15], v[54:55] op_sel_hi:[1,0,1]
	v_pk_fma_f32 v[10:11], v[52:53], v[64:65], v[10:11] op_sel_hi:[0,1,1]
	v_pk_fma_f32 v[12:13], v[52:53], v[48:49], v[16:17] op_sel_hi:[0,1,1]
	ds_write_b128 v1, v[10:13] offset:16384
	s_waitcnt vmcnt(3)
	v_lshlrev_b32_e32 v88, 16, v224
	v_and_b32_e32 v89, 0xffff0000, v224
	s_waitcnt vmcnt(2)
	v_mul_f32_e32 v2, 0x3fb8aa3b, v232
	v_exp_f32_e32 v2, v2
	v_lshlrev_b32_e32 v90, 16, v225
	v_and_b32_e32 v91, 0xffff0000, v225
	s_waitcnt vmcnt(0)
; __device__ __forceinline__ void store2_wt(void* p, unsigned v) { asm volatile("global_store_short %0, %1, off sc1" :: "v"(p), "v"(v) : "memory"); }
; #define LAS __attribute__((address_space(3)))
; #define LDS_SYNC() do { asm volatile("s_waitcnt lgkmcnt(0)" ::: "memory"); __builtin_amdgcn_s_barrier(); asm volatile("" ::: "memory"); } while (0)
; __device__ __forceinline__ unsigned f2bf(float f) { unsigned u = __builtin_bit_cast(unsigned, f); return (u + 0x7fffu + ((u >> 16) & 1u)) >> 16; }
; __device__ __forceinline__ float ex2(float x) { return __builtin_amdgcn_exp2f(x); }
; __device__ __forceinline__ void hgrn_sample_unit(int unit, LAS unsigned char* lds, const float* sh, const float* HLF, const bf16* HQ, const bf16* HV, const bf16* HG, bf16* MIX, float* ohs, gu32* rdy4) {
;     ...
;     for (int t = 0; t < 4; ++t) {
;         const size_t rb = (size_t)(MP + 4 * b + t) * 512 + h * 128;
;         const v2u vw = *(const v2u*)(HV + rb + 4 * v4);
;         const f32x4 vv = {__builtin_bit_cast(float, vw.x << 16), __builtin_bit_cast(float, vw.x & 0xffff0000u), __builtin_bit_cast(float, vw.y << 16), __builtin_bit_cast(float, vw.y & 0xffff0000u)};
;         f32x4 po = {0.f, 0.f, 0.f, 0.f};
; #pragma unroll
;         for (int i = 0; i < 8; ++i) { const float f = ex2(HLF[rb + 8 * kq + i] * LOG2E_F), q = bf2f(HQ[rb + 8 * kq + i]); S[i] = S[i] * f + vv * (1.0f - f); po += S[i] * q; }
;         *(LAS f32x4*)(OP + (t * 16 + kq) * 128 + 4 * v4) = po;
;     }
;     float* so = ohs + ((size_t)unit * 128 + 8 * kq) * 128 + 4 * v4;
; #pragma unroll
;     for (int i = 0; i < 8; ++i) *(f32x4*)(so + i * 128) = S[i];
;     LDS_SYNC();
;     ...
;     const size_t row = (size_t)(MP + 4 * b + t);
;     pg8::store2_wt(MIX + row * 1024 + 512 + h * 128 + v, (unsigned)f2bf(o * rstd * bf2f(HG[row * 512 + h * 128 + v])));
	v_lshlrev_b32_e32 v14, 16, v240
	v_sub_f32_e32 v10, 1.0, v2
	v_pk_mul_f32 v[16:17], v[10:11], v[88:89] op_sel_hi:[0,1]
	v_pk_mul_f32 v[10:11], v[10:11], v[90:91] op_sel_hi:[0,1]
	v_pk_fma_f32 v[12:13], v[58:59], v[2:3], v[10:11] op_sel_hi:[1,0,1]
	v_pk_fma_f32 v[10:11], v[56:57], v[2:3], v[16:17] op_sel_hi:[1,0,1]
	v_mul_f32_e32 v2, 0x3fb8aa3b, v233
	v_exp_f32_e32 v2, v2
	v_pk_fma_f32 v[52:53], v[14:15], v[10:11], 0 op_sel_hi:[0,1,0]
	v_pk_fma_f32 v[54:55], v[14:15], v[12:13], 0 op_sel_hi:[0,1,0]
	v_and_b32_e32 v18, 0xffff0000, v240
	v_sub_f32_e32 v14, 1.0, v2
	v_pk_mul_f32 v[56:57], v[14:15], v[88:89] op_sel_hi:[0,1]
	v_pk_mul_f32 v[14:15], v[14:15], v[90:91] op_sel_hi:[0,1]
	v_pk_fma_f32 v[16:17], v[62:63], v[2:3], v[14:15] op_sel_hi:[1,0,1]
	v_pk_fma_f32 v[14:15], v[60:61], v[2:3], v[56:57] op_sel_hi:[1,0,1]
	v_mul_f32_e32 v2, 0x3fb8aa3b, v234
	v_exp_f32_e32 v2, v2
	v_pk_fma_f32 v[56:57], v[18:19], v[16:17], v[54:55] op_sel_hi:[0,1,1]
	v_pk_fma_f32 v[58:59], v[18:19], v[14:15], v[52:53] op_sel_hi:[0,1,1]
	v_mul_f32_e32 v6, 0x3fb8aa3b, v236
	v_sub_f32_e32 v18, 1.0, v2
	v_pk_mul_f32 v[52:53], v[18:19], v[88:89] op_sel_hi:[0,1]
	v_pk_mul_f32 v[54:55], v[18:19], v[90:91] op_sel_hi:[0,1]
	v_pk_fma_f32 v[54:55], v[70:71], v[2:3], v[54:55] op_sel_hi:[1,0,1]
	v_pk_fma_f32 v[52:53], v[68:69], v[2:3], v[52:53] op_sel_hi:[1,0,1]
	v_mul_f32_e32 v2, 0x3fb8aa3b, v235
	v_exp_f32_e32 v2, v2
	v_lshlrev_b32_e32 v4, 16, v241
	v_exp_f32_e32 v6, v6
	v_pk_fma_f32 v[58:59], v[4:5], v[52:53], v[58:59] op_sel_hi:[0,1,1]
	v_pk_fma_f32 v[56:57], v[4:5], v[54:55], v[56:57] op_sel_hi:[0,1,1]
	v_sub_f32_e32 v4, 1.0, v2
	v_pk_mul_f32 v[60:61], v[4:5], v[88:89] op_sel_hi:[0,1]
	v_pk_mul_f32 v[4:5], v[4:5], v[90:91] op_sel_hi:[0,1]
	v_and_b32_e32 v18, 0xffff0000, v241
	v_pk_fma_f32 v[4:5], v[74:75], v[2:3], v[4:5] op_sel_hi:[1,0,1]
	v_pk_fma_f32 v[2:3], v[72:73], v[2:3], v[60:61] op_sel_hi:[1,0,1]
	v_pk_fma_f32 v[60:61], v[18:19], v[4:5], v[56:57] op_sel_hi:[0,1,1]
	v_sub_f32_e32 v56, 1.0, v6
	v_pk_mul_f32 v[68:69], v[56:57], v[88:89] op_sel_hi:[0,1]
	v_pk_mul_f32 v[56:57], v[56:57], v[90:91] op_sel_hi:[0,1]
	v_pk_fma_f32 v[18:19], v[18:19], v[2:3], v[58:59] op_sel_hi:[0,1,1]
	v_pk_fma_f32 v[58:59], v[78:79], v[6:7], v[56:57] op_sel_hi:[1,0,1]
	v_pk_fma_f32 v[56:57], v[76:77], v[6:7], v[68:69] op_sel_hi:[1,0,1]
	v_mul_f32_e32 v6, 0x3fb8aa3b, v237
	v_exp_f32_e32 v6, v6
	v_lshlrev_b32_e32 v62, 16, v242
	v_pk_fma_f32 v[68:69], v[62:63], v[58:59], v[60:61] op_sel_hi:[0,1,1]
	v_pk_fma_f32 v[18:19], v[62:63], v[56:57], v[18:19] op_sel_hi:[0,1,1]
	v_sub_f32_e32 v60, 1.0, v6
	v_pk_mul_f32 v[70:71], v[60:61], v[88:89] op_sel_hi:[0,1]
	v_pk_mul_f32 v[60:61], v[60:61], v[90:91] op_sel_hi:[0,1]
	v_pk_fma_f32 v[62:63], v[82:83], v[6:7], v[60:61] op_sel_hi:[1,0,1]
	v_pk_fma_f32 v[60:61], v[80:81], v[6:7], v[70:71] op_sel_hi:[1,0,1]
	v_mul_f32_e32 v6, 0x3fb8aa3b, v238
	v_exp_f32_e32 v6, v6
	v_and_b32_e32 v20, 0xffff0000, v242
	v_pk_fma_f32 v[72:73], v[20:21], v[62:63], v[68:69] op_sel_hi:[0,1,1]
	v_pk_fma_f32 v[18:19], v[20:21], v[60:61], v[18:19] op_sel_hi:[0,1,1]
	v_sub_f32_e32 v20, 1.0, v6
	v_pk_mul_f32 v[68:69], v[20:21], v[88:89] op_sel_hi:[0,1]
	v_pk_mul_f32 v[70:71], v[20:21], v[90:91] op_sel_hi:[0,1]
	v_pk_fma_f32 v[70:71], v[86:87], v[6:7], v[70:71] op_sel_hi:[1,0,1]
	v_pk_fma_f32 v[68:69], v[84:85], v[6:7], v[68:69] op_sel_hi:[1,0,1]
	v_mul_f32_e32 v6, 0x3fb8aa3b, v239
	v_exp_f32_e32 v6, v6
	v_lshlrev_b32_e32 v8, 16, v243
	v_pk_fma_f32 v[18:19], v[8:9], v[68:69], v[18:19] op_sel_hi:[0,1,1]
	v_pk_fma_f32 v[72:73], v[8:9], v[70:71], v[72:73] op_sel_hi:[0,1,1]
	v_sub_f32_e32 v8, 1.0, v6
	v_and_b32_e32 v74, 0xffff0000, v243
	v_pk_mul_f32 v[20:21], v[8:9], v[88:89] op_sel_hi:[0,1]
	v_pk_mul_f32 v[8:9], v[8:9], v[90:91] op_sel_hi:[0,1]
	v_pk_fma_f32 v[8:9], v[48:49], v[6:7], v[8:9] op_sel_hi:[1,0,1]
	v_pk_fma_f32 v[6:7], v[64:65], v[6:7], v[20:21] op_sel_hi:[1,0,1]
	v_pk_fma_f32 v[20:21], v[74:75], v[8:9], v[72:73] op_sel_hi:[0,1,1]
	v_pk_fma_f32 v[18:19], v[74:75], v[6:7], v[18:19] op_sel_hi:[0,1,1]
	ds_write_b128 v1, v[18:21] offset:24576
	v_lshl_add_u64 v[18:19], v[32:33], 0, v[28:29]
	v_add_u32_e32 v248, s22, v35
	v_ashrrev_i32_e32 v249, 31, v248
	s_lshl_b32 s98, s12, 1
	s_mov_b32 s99, s13
	v_lshlrev_b64 v[250:251], 10, v[248:249]
	v_lshl_add_u64 v[250:251], s[18:19], 0, v[250:251]
	v_lshl_add_u64 v[250:251], v[250:251], 0, s[98:99]
	v_lshl_add_u64 v[250:251], v[250:251], 0, v[24:25]
	global_load_ushort v252, v[250:251], off
	global_store_dwordx4 v[18:19], v[10:13], off offset:-2048
	global_store_dwordx4 v[18:19], v[14:17], off offset:-1536
	global_store_dwordx4 v[18:19], v[52:55], off offset:-1024
	global_store_dwordx4 v[18:19], v[2:5], off offset:-512
	global_store_dwordx4 v[18:19], v[56:59], off
	global_store_dwordx4 v[18:19], v[60:63], off offset:512
	global_store_dwordx4 v[18:19], v[68:71], off offset:1024
	global_store_dwordx4 v[18:19], v[6:9], off offset:1536
	s_waitcnt lgkmcnt(0)
	s_barrier
; __device__ __forceinline__ float wave_sum(float v) {
; #pragma unroll
;     for (int o = 1; o < 64; o <<= 1) v += __shfl_xor(v, o);
;     return v;
; __device__ __forceinline__ void hgrn_sample_unit(int unit, LAS unsigned char* lds, const float* sh, const float* HLF, const bf16* HQ, const bf16* HV, const bf16* HG, bf16* MIX, float* ohs, gu32* rdy4) {
;     ...
;     const int t = tid >> 7, v = tid & 127; float o = 0.f;
; #pragma unroll
;     for (int q = 0; q < 16; ++q) o += OP[(t * 16 + q) * 128 + v];
;     const float ps = wave_sum(o * o);
;     if ((tid & 63) == 0) PS[wid] = ps;
	ds_read2st64_b32 v[2:3], v36 offset1:2
	ds_read2st64_b32 v[4:5], v36 offset0:4 offset1:6
	ds_read2st64_b32 v[6:7], v36 offset0:8 offset1:10
	s_waitcnt lgkmcnt(2)
	v_add_f32_e32 v2, 0, v2
	v_add_f32_e32 v2, v2, v3
	s_waitcnt lgkmcnt(1)
	v_add_f32_e32 v4, v2, v4
	ds_read2st64_b32 v[2:3], v36 offset0:12 offset1:14
	v_add_f32_e32 v4, v4, v5
	s_waitcnt lgkmcnt(1)
	v_add_f32_e32 v6, v4, v6
	ds_read2st64_b32 v[4:5], v36 offset0:16 offset1:18
	v_add_f32_e32 v6, v6, v7
	s_waitcnt lgkmcnt(1)
	v_add_f32_e32 v2, v6, v2
	v_add_f32_e32 v6, v2, v3
	ds_read2st64_b32 v[2:3], v36 offset0:20 offset1:22
	s_waitcnt lgkmcnt(1)
	v_add_f32_e32 v4, v6, v4
	ds_read2st64_b32 v[6:7], v36 offset0:24 offset1:26
	v_add_f32_e32 v8, v4, v5
	ds_read2st64_b32 v[4:5], v36 offset0:28 offset1:30
	s_waitcnt lgkmcnt(2)
	v_add_f32_e32 v2, v8, v2
	v_add_f32_e32 v2, v2, v3
	s_waitcnt lgkmcnt(1)
	v_add_f32_e32 v2, v2, v6
	v_add_f32_e32 v2, v2, v7
	s_waitcnt lgkmcnt(0)
	v_add_f32_e32 v2, v2, v4
	v_add_f32_e32 v2, v2, v5
	v_cndmask_b32_e32 v4, v37, v39, vcc
	v_mul_f32_e32 v3, v2, v2
	v_lshlrev_b32_e32 v4, 2, v4
	s_nop 1
	v_mov_b32_dpp v3, v3 quad_perm:[1,0,3,2] row_mask:0xf bank_mask:0xf
	v_cmp_lt_i32_e32 vcc, v40, v38
	s_waitcnt lgkmcnt(0)
	v_fmac_f32_e32 v3, v2, v2
	v_cndmask_b32_e32 v4, v37, v40, vcc
	v_lshlrev_b32_e32 v4, 2, v4
	v_mov_b32_dpp v4, v3 quad_perm:[2,3,0,1] row_mask:0xf bank_mask:0xf
	v_cmp_lt_i32_e32 vcc, v41, v38
	s_waitcnt lgkmcnt(0)
	v_add_f32_e32 v3, v3, v4
	v_cndmask_b32_e32 v4, v37, v41, vcc
	v_lshlrev_b32_e32 v4, 2, v4
	v_mov_b32_dpp v4, v3 row_shr:4 row_mask:0xf bank_mask:0xa
	v_mov_b32_dpp v4, v3 row_shl:4 row_mask:0xf bank_mask:0x5
	v_cmp_lt_i32_e32 vcc, v42, v38
	s_waitcnt lgkmcnt(0)
	v_add_f32_e32 v3, v3, v4
	v_cndmask_b32_e32 v4, v37, v42, vcc
	v_lshlrev_b32_e32 v4, 2, v4
	v_mov_b32_dpp v4, v3 row_ror:8 row_mask:0xf bank_mask:0xf
	v_cmp_lt_i32_e32 vcc, v43, v38
	s_waitcnt lgkmcnt(0)
	v_add_f32_e32 v3, v3, v4
	v_cndmask_b32_e32 v4, v37, v43, vcc
	v_lshlrev_b32_e32 v4, 2, v4
	v_mov_b32_e32 v4, v3
	s_nop 1
	v_permlane16_swap_b32_e32 v4, v3
	v_cmp_lt_i32_e32 vcc, v44, v38
	s_waitcnt lgkmcnt(0)
	v_add_f32_e32 v3, v3, v4
	v_cndmask_b32_e32 v4, v37, v44, vcc
	v_lshlrev_b32_e32 v4, 2, v4
	v_mov_b32_e32 v4, v3
	s_nop 1
	v_permlane32_swap_b32_e32 v4, v3
	s_and_saveexec_b64 s[24:25], s[6:7]
	s_cbranch_execz .LBB0_604
	s_waitcnt lgkmcnt(0)
	v_add_f32_e32 v3, v3, v4
	ds_write_b32 v34, v3 offset:32768

; __device__ __forceinline__ unsigned cvt_pk_bf16(float lo, float hi) { f32x2_t v = {lo, hi}; bf16x2_t b = __builtin_convertvector(v, bf16x2_t); return __builtin_bit_cast(unsigned, b); }
; __device__ __forceinline__ float sigm(float x) { return __builtin_amdgcn_rcpf(1.0f + __builtin_amdgcn_exp2f(-x * LOG2E)); }
;     __device__ __forceinline__ void operator()(const f32x4 (&acc)[2][2][4][2], const Unit& u, int wr, int wc, int fr, int fq) const {
;     ...
;                         const int row = row0 + ai * HALF + m * 16, rl = row - MPR, bs = rl >> 2, t = rl & 3;
;                         const f32x4 a = acc[ai][0][m][n] * rs[ai][m], uu = acc[ai][1][m][n] * rs[ai][m]; f32x4 gg, s0 = {0.f, 0.f, 0.f, 0.f}, s1 = {0.f, 0.f, 0.f, 0.f};
;                         const float* sc = sconv + (size_t)bs * 2 * 2816 + colt + 4 * n;
;                         if (t == 0) s0 = *(const f32x4*)sc;
;                         if (t <= 1) s1 = *(const f32x4*)(sc + 2816);
; #pragma unroll
;                         for (int j = 0; j < 4; ++j) {
;                             const float up1 = __shfl_up(a[j], 1, 16), up2 = __shfl_up(a[j], 2, 16);
;                             const float p1 = t == 0 ? s1[j] : up1, p2 = t == 0 ? s0[j] : (t == 1 ? s1[j] : up2);
;                             const float c = bb[j] + w0[j] * p2 + w1[j] * p1 + w2[j] * a[j];
;                             gg[j] = c * sigm(c) * uu[j];
;                         }
;                         *(u32x2*)(G + (size_t)row * 2816 + colt + 4 * n) = (u32x2){cvt_pk_bf16(gg[0], gg[1]), cvt_pk_bf16(gg[2], gg[3])};
;                         if (t >= 2) *(f32x4*)(ocs + (size_t)(bs * 2 + t - 2) * 2816 + colt + 4 * n) = a;
.LBB0_900:
	s_or_b64 exec, exec, s[8:9]
	v_add_u32_e32 v154, -1, v1
	v_and_b32_e32 v155, 0x70, v1
	v_cmp_lt_i32_e32 vcc, v154, v155
	v_cmp_eq_u32_e64 s[10:11], 1, v156
	v_cmp_lt_u32_e64 s[8:9], 1, v156
	v_cndmask_b32_e32 v154, v154, v1, vcc
	v_lshlrev_b32_e32 v240, 2, v154
	v_add_u32_e32 v154, -2, v1
	v_cmp_lt_i32_e32 vcc, v154, v155
	v_lshl_add_u32 v171, v171, 1, v179
	s_nop 0
	v_cndmask_b32_e32 v157, v154, v1, vcc
	v_pk_mul_f32 v[154:155], v[126:127], v[184:185] op_sel_hi:[1,0]
	v_lshlrev_b32_e32 v241, 2, v157
	v_mov_b32_e32 v175, v154
	s_nop 0
	v_mov_b32_dpp v175, v154 row_shr:1 row_mask:0xf bank_mask:0xf
	v_mov_b32_e32 v157, v154
	v_mov_b32_dpp v157, v154 row_shr:2 row_mask:0xf bank_mask:0xf
	v_mov_b32_e32 v173, v155
	v_mov_b32_dpp v173, v155 row_shr:1 row_mask:0xf bank_mask:0xf
	v_mov_b32_e32 v177, v155
	v_mov_b32_dpp v177, v155 row_shr:2 row_mask:0xf bank_mask:0xf
	s_waitcnt vmcnt(0) lgkmcnt(3)
	v_cndmask_b32_e64 v196, v175, v150, s[6:7]
	s_waitcnt lgkmcnt(2)
	v_cndmask_b32_e64 v150, v157, v150, s[10:11]
	v_pk_mul_f32 v[156:157], v[128:129], v[184:185] op_sel_hi:[1,0]
	s_waitcnt lgkmcnt(1)
	v_cndmask_b32_e64 v197, v173, v151, s[6:7]
	s_waitcnt lgkmcnt(0)
	v_cndmask_b32_e64 v151, v177, v151, s[10:11]
	v_mov_b32_e32 v173, v157
	v_mov_b32_dpp v173, v157 row_shr:1 row_mask:0xf bank_mask:0xf
	v_mov_b32_e32 v175, v156
	v_mov_b32_dpp v175, v156 row_shr:1 row_mask:0xf bank_mask:0xf
	v_mov_b32_e32 v177, v156
	v_mov_b32_dpp v177, v156 row_shr:2 row_mask:0xf bank_mask:0xf
	v_mov_b32_e32 v181, v157
	v_mov_b32_dpp v181, v157 row_shr:2 row_mask:0xf bank_mask:0xf
	v_cndmask_b32_e64 v147, v151, v147, s[6:7]
	v_cndmask_b32_e64 v146, v150, v146, s[6:7]
	v_pk_fma_f32 v[146:147], v[130:131], v[146:147], v[142:143]
	s_nop 0
	v_pk_fma_f32 v[146:147], v[134:135], v[196:197], v[146:147]
	s_waitcnt lgkmcnt(3)
	v_cndmask_b32_e64 v197, v173, v153, s[6:7]
	s_waitcnt lgkmcnt(2)
	v_cndmask_b32_e64 v196, v175, v152, s[6:7]
	s_waitcnt lgkmcnt(1)
	v_cndmask_b32_e64 v152, v177, v152, s[10:11]
	s_waitcnt lgkmcnt(0)
	v_cndmask_b32_e64 v153, v181, v153, s[10:11]
	v_cndmask_b32_e64 v149, v153, v149, s[6:7]
	v_cndmask_b32_e64 v148, v152, v148, s[6:7]
	v_pk_fma_f32 v[148:149], v[132:133], v[148:149], v[144:145]
	v_pk_fma_f32 v[146:147], v[154:155], v[138:139], v[146:147]
	v_pk_fma_f32 v[148:149], v[136:137], v[196:197], v[148:149]
	v_mul_f32_e32 v150, 0xbfb8aa3b, v146
	v_mul_f32_e32 v151, 0xbfb8aa3b, v147
	v_pk_fma_f32 v[148:149], v[156:157], v[140:141], v[148:149]
	v_exp_f32_e32 v150, v150
	v_exp_f32_e32 v151, v151
	v_mul_f32_e32 v152, 0xbfb8aa3b, v148
	v_mul_f32_e32 v153, 0xbfb8aa3b, v149
	v_exp_f32_e32 v152, v152
	v_exp_f32_e32 v153, v153
	v_add_f32_e32 v150, 1.0, v150
	v_add_f32_e32 v151, 1.0, v151
	v_rcp_f32_e32 v150, v150
	v_rcp_f32_e32 v151, v151
	v_add_f32_e32 v152, 1.0, v152
	v_add_f32_e32 v153, 1.0, v153
	v_rcp_f32_e32 v152, v152
	v_rcp_f32_e32 v153, v153
	v_pk_mul_f32 v[146:147], v[146:147], v[150:151]
	v_pk_mul_f32 v[150:151], v[94:95], v[184:185] op_sel_hi:[1,0]
	v_pk_mul_f32 v[148:149], v[148:149], v[152:153]
	v_pk_mul_f32 v[146:147], v[150:151], v[146:147]
	v_pk_mul_f32 v[150:151], v[96:97], v[184:185] op_sel_hi:[1,0]
	v_cvt_pk_bf16_f32 v146, v146, v147
	v_pk_mul_f32 v[148:149], v[150:151], v[148:149]
	s_nop 0
	v_cvt_pk_bf16_f32 v147, v148, v149
	v_mov_b64_e32 v[148:149], s[42:43]
	v_mad_i64_i32 v[148:149], s[20:21], v192, s47, v[148:149]
	v_lshl_add_u64 v[214:215], v[168:169], 1, v[148:149]
	global_store_dwordx2 v[214:215], v[146:147], off
	s_and_saveexec_b64 s[88:89], s[8:9]
	s_cbranch_execz .LBB0_902
	v_mov_b64_e32 v[146:147], s[66:67]
	v_mad_i64_i32 v[146:147], s[20:21], v171, s48, v[146:147]
	v_lshl_add_u64 v[146:147], v[168:169], 2, v[146:147]
	global_store_dwordx4 v[146:147], v[154:157], off

; __device__ __forceinline__ unsigned cvt_pk_bf16(float lo, float hi) { f32x2_t v = {lo, hi}; bf16x2_t b = __builtin_convertvector(v, bf16x2_t); return __builtin_bit_cast(unsigned, b); }
; __device__ __forceinline__ float sigm(float x) { return __builtin_amdgcn_rcpf(1.0f + __builtin_amdgcn_exp2f(-x * LOG2E)); }
;     __device__ __forceinline__ void operator()(const f32x4 (&acc)[2][2][4][2], const Unit& u, int wr, int wc, int fr, int fq) const {
;     ...
;                         const int row = row0 + ai * HALF + m * 16, rl = row - MPR, bs = rl >> 2, t = rl & 3;
;                         const f32x4 a = acc[ai][0][m][n] * rs[ai][m], uu = acc[ai][1][m][n] * rs[ai][m]; f32x4 gg, s0 = {0.f, 0.f, 0.f, 0.f}, s1 = {0.f, 0.f, 0.f, 0.f};
;                         const float* sc = sconv + (size_t)bs * 2 * 2816 + colt + 4 * n;
;                         if (t == 0) s0 = *(const f32x4*)sc;
;                         if (t <= 1) s1 = *(const f32x4*)(sc + 2816);
; #pragma unroll
;                         for (int j = 0; j < 4; ++j) {
;                             const float up1 = __shfl_up(a[j], 1, 16), up2 = __shfl_up(a[j], 2, 16);
;                             const float p1 = t == 0 ? s1[j] : up1, p2 = t == 0 ? s0[j] : (t == 1 ? s1[j] : up2);
;                             const float c = bb[j] + w0[j] * p2 + w1[j] * p1 + w2[j] * a[j];
;                             gg[j] = c * sigm(c) * uu[j];
;                         }
;                         *(u32x2*)(G + (size_t)row * 2816 + colt + 4 * n) = (u32x2){cvt_pk_bf16(gg[0], gg[1]), cvt_pk_bf16(gg[2], gg[3])};
;                         if (t >= 2) *(f32x4*)(ocs + (size_t)(bs * 2 + t - 2) * 2816 + colt + 4 * n) = a;
.LBB0_906:
	s_or_b64 exec, exec, s[88:89]
	v_pk_mul_f32 v[154:155], v[118:119], v[182:183] op_sel_hi:[1,0]
	v_mov_b32_e32 v156, v155
	s_nop 0
	v_mov_b32_dpp v156, v155 row_shr:1 row_mask:0xf bank_mask:0xf
	v_mov_b32_e32 v175, v154
	v_mov_b32_dpp v175, v154 row_shr:1 row_mask:0xf bank_mask:0xf
	v_mov_b32_e32 v177, v154
	v_mov_b32_dpp v177, v154 row_shr:2 row_mask:0xf bank_mask:0xf
	v_mov_b32_e32 v181, v155
	v_mov_b32_dpp v181, v155 row_shr:2 row_mask:0xf bank_mask:0xf
	v_lshl_add_u32 v173, v173, 1, v179
	s_waitcnt vmcnt(0) lgkmcnt(3)
	v_cndmask_b32_e64 v157, v156, v151, s[6:7]
	s_waitcnt lgkmcnt(2)
	v_cndmask_b32_e64 v156, v175, v150, s[6:7]
	s_waitcnt lgkmcnt(1)
	v_cndmask_b32_e64 v150, v177, v150, s[10:11]
	s_waitcnt lgkmcnt(0)
	v_cndmask_b32_e64 v151, v181, v151, s[10:11]
	v_cndmask_b32_e64 v147, v151, v147, s[6:7]
	v_cndmask_b32_e64 v146, v150, v146, s[6:7]
	v_pk_fma_f32 v[146:147], v[130:131], v[146:147], v[142:143]
	s_nop 0
	v_pk_fma_f32 v[146:147], v[134:135], v[156:157], v[146:147]
	v_pk_mul_f32 v[156:157], v[120:121], v[182:183] op_sel_hi:[1,0]
	v_mov_b32_e32 v175, v157
	s_nop 0
	v_mov_b32_dpp v175, v157 row_shr:1 row_mask:0xf bank_mask:0xf
	v_mov_b32_e32 v177, v156
	v_mov_b32_dpp v177, v156 row_shr:1 row_mask:0xf bank_mask:0xf
	v_mov_b32_e32 v181, v156
	v_mov_b32_dpp v181, v156 row_shr:2 row_mask:0xf bank_mask:0xf
	v_mov_b32_e32 v183, v157
	v_mov_b32_dpp v183, v157 row_shr:2 row_mask:0xf bank_mask:0xf
	v_pk_fma_f32 v[146:147], v[154:155], v[138:139], v[146:147]
	s_waitcnt lgkmcnt(3)
	v_cndmask_b32_e64 v199, v175, v153, s[6:7]
	s_waitcnt lgkmcnt(2)
	v_cndmask_b32_e64 v198, v177, v152, s[6:7]
	s_waitcnt lgkmcnt(1)
	v_cndmask_b32_e64 v152, v181, v152, s[10:11]
	s_waitcnt lgkmcnt(0)
	v_cndmask_b32_e64 v153, v183, v153, s[10:11]
	v_cndmask_b32_e64 v149, v153, v149, s[6:7]
	v_cndmask_b32_e64 v148, v152, v148, s[6:7]
	v_pk_fma_f32 v[148:149], v[132:133], v[148:149], v[144:145]
	v_mul_f32_e32 v150, 0xbfb8aa3b, v146
	v_pk_fma_f32 v[148:149], v[136:137], v[198:199], v[148:149]
	v_mul_f32_e32 v151, 0xbfb8aa3b, v147
	v_pk_fma_f32 v[148:149], v[156:157], v[140:141], v[148:149]
	v_exp_f32_e32 v150, v150
	v_exp_f32_e32 v151, v151
	v_mul_f32_e32 v152, 0xbfb8aa3b, v148
	v_mul_f32_e32 v153, 0xbfb8aa3b, v149
	v_exp_f32_e32 v152, v152
	v_exp_f32_e32 v153, v153
	v_add_f32_e32 v150, 1.0, v150
	v_add_f32_e32 v151, 1.0, v151
	v_rcp_f32_e32 v150, v150
	v_rcp_f32_e32 v151, v151
	v_add_f32_e32 v152, 1.0, v152
	v_add_f32_e32 v153, 1.0, v153
	v_rcp_f32_e32 v152, v152
	v_rcp_f32_e32 v153, v153
	v_pk_mul_f32 v[146:147], v[146:147], v[150:151]
	v_pk_mul_f32 v[150:151], v[86:87], v[182:183] op_sel_hi:[1,0]
	v_pk_mul_f32 v[148:149], v[148:149], v[152:153]
	v_pk_mul_f32 v[146:147], v[150:151], v[146:147]
	v_pk_mul_f32 v[150:151], v[88:89], v[182:183] op_sel_hi:[1,0]
	v_cvt_pk_bf16_f32 v146, v146, v147
	v_pk_mul_f32 v[148:149], v[150:151], v[148:149]
	s_nop 0
	v_cvt_pk_bf16_f32 v147, v148, v149
	v_mov_b64_e32 v[148:149], s[42:43]
	v_mad_i64_i32 v[148:149], s[20:21], v190, s47, v[148:149]
	v_lshl_add_u64 v[216:217], v[168:169], 1, v[148:149]
	global_store_dwordx2 v[216:217], v[146:147], off
	s_and_saveexec_b64 s[88:89], s[8:9]
	s_cbranch_execz .LBB0_908
	v_mov_b64_e32 v[146:147], s[66:67]
	v_mad_i64_i32 v[146:147], s[20:21], v173, s48, v[146:147]
	v_lshl_add_u64 v[146:147], v[168:169], 2, v[146:147]
	global_store_dwordx4 v[146:147], v[154:157], off

; __device__ __forceinline__ unsigned cvt_pk_bf16(float lo, float hi) { f32x2_t v = {lo, hi}; bf16x2_t b = __builtin_convertvector(v, bf16x2_t); return __builtin_bit_cast(unsigned, b); }
; __device__ __forceinline__ float sigm(float x) { return __builtin_amdgcn_rcpf(1.0f + __builtin_amdgcn_exp2f(-x * LOG2E)); }
;     __device__ __forceinline__ void operator()(const f32x4 (&acc)[2][2][4][2], const Unit& u, int wr, int wc, int fr, int fq) const {
;     ...
;                         const int row = row0 + ai * HALF + m * 16, rl = row - MPR, bs = rl >> 2, t = rl & 3;
;                         const f32x4 a = acc[ai][0][m][n] * rs[ai][m], uu = acc[ai][1][m][n] * rs[ai][m]; f32x4 gg, s0 = {0.f, 0.f, 0.f, 0.f}, s1 = {0.f, 0.f, 0.f, 0.f};
;                         const float* sc = sconv + (size_t)bs * 2 * 2816 + colt + 4 * n;
;                         if (t == 0) s0 = *(const f32x4*)sc;
;                         if (t <= 1) s1 = *(const f32x4*)(sc + 2816);
; #pragma unroll
;                         for (int j = 0; j < 4; ++j) {
;                             const float up1 = __shfl_up(a[j], 1, 16), up2 = __shfl_up(a[j], 2, 16);
;                             const float p1 = t == 0 ? s1[j] : up1, p2 = t == 0 ? s0[j] : (t == 1 ? s1[j] : up2);
;                             const float c = bb[j] + w0[j] * p2 + w1[j] * p1 + w2[j] * a[j];
;                             gg[j] = c * sigm(c) * uu[j];
;                         }
;                         *(u32x2*)(G + (size_t)row * 2816 + colt + 4 * n) = (u32x2){cvt_pk_bf16(gg[0], gg[1]), cvt_pk_bf16(gg[2], gg[3])};
;                         if (t >= 2) *(f32x4*)(ocs + (size_t)(bs * 2 + t - 2) * 2816 + colt + 4 * n) = a;
.LBB0_912:
	s_or_b64 exec, exec, s[88:89]
	v_pk_mul_f32 v[154:155], v[110:111], v[180:181] op_sel_hi:[1,0]
	v_mov_b32_e32 v156, v155
	s_nop 0
	v_mov_b32_dpp v156, v155 row_shr:1 row_mask:0xf bank_mask:0xf
	v_mov_b32_e32 v177, v154
	v_mov_b32_dpp v177, v154 row_shr:1 row_mask:0xf bank_mask:0xf
	v_mov_b32_e32 v181, v154
	v_mov_b32_dpp v181, v154 row_shr:2 row_mask:0xf bank_mask:0xf
	v_mov_b32_e32 v183, v155
	v_mov_b32_dpp v183, v155 row_shr:2 row_mask:0xf bank_mask:0xf
	v_lshl_add_u32 v175, v175, 1, v179
	s_waitcnt vmcnt(0) lgkmcnt(3)
	v_cndmask_b32_e64 v157, v156, v151, s[6:7]
	s_waitcnt lgkmcnt(2)
	v_cndmask_b32_e64 v156, v177, v150, s[6:7]
	s_waitcnt lgkmcnt(1)
	v_cndmask_b32_e64 v150, v181, v150, s[10:11]
	s_waitcnt lgkmcnt(0)
	v_cndmask_b32_e64 v151, v183, v151, s[10:11]
	v_cndmask_b32_e64 v147, v151, v147, s[6:7]
	v_cndmask_b32_e64 v146, v150, v146, s[6:7]
	v_pk_fma_f32 v[146:147], v[130:131], v[146:147], v[142:143]
	s_nop 0
	v_pk_fma_f32 v[146:147], v[134:135], v[156:157], v[146:147]
	v_pk_mul_f32 v[156:157], v[112:113], v[180:181] op_sel_hi:[1,0]
	v_mov_b32_e32 v177, v157
	s_nop 0
	v_mov_b32_dpp v177, v157 row_shr:1 row_mask:0xf bank_mask:0xf
	v_mov_b32_e32 v181, v156
	v_mov_b32_dpp v181, v156 row_shr:1 row_mask:0xf bank_mask:0xf
	v_mov_b32_e32 v183, v156
	v_mov_b32_dpp v183, v156 row_shr:2 row_mask:0xf bank_mask:0xf
	v_mov_b32_e32 v185, v157
	v_mov_b32_dpp v185, v157 row_shr:2 row_mask:0xf bank_mask:0xf
	v_pk_fma_f32 v[146:147], v[154:155], v[138:139], v[146:147]
	s_waitcnt lgkmcnt(3)
	v_cndmask_b32_e64 v201, v177, v153, s[6:7]
	s_waitcnt lgkmcnt(2)
	v_cndmask_b32_e64 v200, v181, v152, s[6:7]
	s_waitcnt lgkmcnt(1)
	v_cndmask_b32_e64 v152, v183, v152, s[10:11]
	s_waitcnt lgkmcnt(0)
	v_cndmask_b32_e64 v153, v185, v153, s[10:11]
	v_cndmask_b32_e64 v149, v153, v149, s[6:7]
	v_cndmask_b32_e64 v148, v152, v148, s[6:7]
	v_pk_fma_f32 v[148:149], v[132:133], v[148:149], v[144:145]
	v_mul_f32_e32 v150, 0xbfb8aa3b, v146
	v_pk_fma_f32 v[148:149], v[136:137], v[200:201], v[148:149]
	v_mul_f32_e32 v151, 0xbfb8aa3b, v147
	v_pk_fma_f32 v[148:149], v[156:157], v[140:141], v[148:149]
	v_exp_f32_e32 v150, v150
	v_exp_f32_e32 v151, v151
	v_mul_f32_e32 v152, 0xbfb8aa3b, v148
	v_mul_f32_e32 v153, 0xbfb8aa3b, v149
	v_exp_f32_e32 v152, v152
	v_exp_f32_e32 v153, v153
	v_add_f32_e32 v150, 1.0, v150
	v_add_f32_e32 v151, 1.0, v151
	v_rcp_f32_e32 v150, v150
	v_rcp_f32_e32 v151, v151
	v_add_f32_e32 v152, 1.0, v152
	v_add_f32_e32 v153, 1.0, v153
	v_rcp_f32_e32 v152, v152
	v_rcp_f32_e32 v153, v153
	v_pk_mul_f32 v[146:147], v[146:147], v[150:151]
	v_pk_mul_f32 v[150:151], v[78:79], v[180:181] op_sel_hi:[1,0]
	v_pk_mul_f32 v[148:149], v[148:149], v[152:153]
	v_pk_mul_f32 v[146:147], v[150:151], v[146:147]
	v_pk_mul_f32 v[150:151], v[80:81], v[180:181] op_sel_hi:[1,0]
	v_cvt_pk_bf16_f32 v146, v146, v147
	v_pk_mul_f32 v[148:149], v[150:151], v[148:149]
	s_nop 0
	v_cvt_pk_bf16_f32 v147, v148, v149
	v_mov_b64_e32 v[148:149], s[42:43]
	v_mad_i64_i32 v[148:149], s[20:21], v188, s47, v[148:149]
	v_lshl_add_u64 v[218:219], v[168:169], 1, v[148:149]
	global_store_dwordx2 v[218:219], v[146:147], off
	s_and_saveexec_b64 s[88:89], s[8:9]
	s_cbranch_execz .LBB0_914
	v_mov_b64_e32 v[146:147], s[66:67]
	v_mad_i64_i32 v[146:147], s[20:21], v175, s48, v[146:147]
	v_lshl_add_u64 v[146:147], v[168:169], 2, v[146:147]
	global_store_dwordx4 v[146:147], v[154:157], off

; __device__ __forceinline__ unsigned cvt_pk_bf16(float lo, float hi) { f32x2_t v = {lo, hi}; bf16x2_t b = __builtin_convertvector(v, bf16x2_t); return __builtin_bit_cast(unsigned, b); }
; __device__ __forceinline__ float sigm(float x) { return __builtin_amdgcn_rcpf(1.0f + __builtin_amdgcn_exp2f(-x * LOG2E)); }
;     __device__ __forceinline__ void operator()(const f32x4 (&acc)[2][2][4][2], const Unit& u, int wr, int wc, int fr, int fq) const {
;     ...
;                         const int row = row0 + ai * HALF + m * 16, rl = row - MPR, bs = rl >> 2, t = rl & 3;
;                         const f32x4 a = acc[ai][0][m][n] * rs[ai][m], uu = acc[ai][1][m][n] * rs[ai][m]; f32x4 gg, s0 = {0.f, 0.f, 0.f, 0.f}, s1 = {0.f, 0.f, 0.f, 0.f};
;                         const float* sc = sconv + (size_t)bs * 2 * 2816 + colt + 4 * n;
;                         if (t == 0) s0 = *(const f32x4*)sc;
;                         if (t <= 1) s1 = *(const f32x4*)(sc + 2816);
; #pragma unroll
;                         for (int j = 0; j < 4; ++j) {
;                             const float up1 = __shfl_up(a[j], 1, 16), up2 = __shfl_up(a[j], 2, 16);
;                             const float p1 = t == 0 ? s1[j] : up1, p2 = t == 0 ? s0[j] : (t == 1 ? s1[j] : up2);
;                             const float c = bb[j] + w0[j] * p2 + w1[j] * p1 + w2[j] * a[j];
;                             gg[j] = c * sigm(c) * uu[j];
;                         }
;                         *(u32x2*)(G + (size_t)row * 2816 + colt + 4 * n) = (u32x2){cvt_pk_bf16(gg[0], gg[1]), cvt_pk_bf16(gg[2], gg[3])};
;                         if (t >= 2) *(f32x4*)(ocs + (size_t)(bs * 2 + t - 2) * 2816 + colt + 4 * n) = a;
.LBB0_918:
	s_or_b64 exec, exec, s[88:89]
	v_pk_mul_f32 v[154:155], v[102:103], v[178:179] op_sel_hi:[1,0]
	v_mov_b32_e32 v156, v155
	s_nop 0
	v_mov_b32_dpp v156, v155 row_shr:1 row_mask:0xf bank_mask:0xf
	v_mov_b32_e32 v181, v154
	v_mov_b32_dpp v181, v154 row_shr:1 row_mask:0xf bank_mask:0xf
	v_mov_b32_e32 v183, v154
	v_mov_b32_dpp v183, v154 row_shr:2 row_mask:0xf bank_mask:0xf
	v_mov_b32_e32 v185, v155
	v_mov_b32_dpp v185, v155 row_shr:2 row_mask:0xf bank_mask:0xf
	v_lshl_add_u32 v177, v177, 1, v179
	s_waitcnt vmcnt(0) lgkmcnt(3)
	v_cndmask_b32_e64 v157, v156, v151, s[6:7]
	s_waitcnt lgkmcnt(2)
	v_cndmask_b32_e64 v156, v181, v150, s[6:7]
	s_waitcnt lgkmcnt(1)
	v_cndmask_b32_e64 v150, v183, v150, s[10:11]
	s_waitcnt lgkmcnt(0)
	v_cndmask_b32_e64 v151, v185, v151, s[10:11]
	v_cndmask_b32_e64 v147, v151, v147, s[6:7]
	v_cndmask_b32_e64 v146, v150, v146, s[6:7]
	v_pk_fma_f32 v[146:147], v[130:131], v[146:147], v[142:143]
	s_nop 0
	v_pk_fma_f32 v[146:147], v[134:135], v[156:157], v[146:147]
	v_pk_mul_f32 v[156:157], v[104:105], v[178:179] op_sel_hi:[1,0]
	v_mov_b32_e32 v181, v157
	s_nop 0
	v_mov_b32_dpp v181, v157 row_shr:1 row_mask:0xf bank_mask:0xf
	v_mov_b32_e32 v183, v156
	v_mov_b32_dpp v183, v156 row_shr:1 row_mask:0xf bank_mask:0xf
	v_mov_b32_e32 v185, v156
	v_mov_b32_dpp v185, v156 row_shr:2 row_mask:0xf bank_mask:0xf
	v_mov_b32_e32 v208, v157
	v_mov_b32_dpp v208, v157 row_shr:2 row_mask:0xf bank_mask:0xf
	v_pk_fma_f32 v[146:147], v[154:155], v[138:139], v[146:147]
	s_waitcnt lgkmcnt(3)
	v_cndmask_b32_e64 v205, v181, v153, s[6:7]
	s_waitcnt lgkmcnt(2)
	v_cndmask_b32_e64 v204, v183, v152, s[6:7]
	s_waitcnt lgkmcnt(1)
	v_cndmask_b32_e64 v152, v185, v152, s[10:11]
	s_waitcnt lgkmcnt(0)
	v_cndmask_b32_e64 v153, v208, v153, s[10:11]
	v_cndmask_b32_e64 v149, v153, v149, s[6:7]
	v_cndmask_b32_e64 v148, v152, v148, s[6:7]
	v_pk_fma_f32 v[148:149], v[132:133], v[148:149], v[144:145]
	v_mul_f32_e32 v150, 0xbfb8aa3b, v146
	v_pk_fma_f32 v[148:149], v[136:137], v[204:205], v[148:149]
	v_mul_f32_e32 v151, 0xbfb8aa3b, v147
	v_pk_fma_f32 v[148:149], v[156:157], v[140:141], v[148:149]
	v_exp_f32_e32 v150, v150
	v_exp_f32_e32 v151, v151
	v_mul_f32_e32 v152, 0xbfb8aa3b, v148
	v_mul_f32_e32 v153, 0xbfb8aa3b, v149
	v_exp_f32_e32 v152, v152
	v_exp_f32_e32 v153, v153
	v_add_f32_e32 v150, 1.0, v150
	v_add_f32_e32 v151, 1.0, v151
	v_rcp_f32_e32 v150, v150
	v_rcp_f32_e32 v151, v151
	v_add_f32_e32 v152, 1.0, v152
	v_add_f32_e32 v153, 1.0, v153
	v_rcp_f32_e32 v152, v152
	v_rcp_f32_e32 v153, v153
	v_pk_mul_f32 v[146:147], v[146:147], v[150:151]
	v_pk_mul_f32 v[150:151], v[70:71], v[178:179] op_sel_hi:[1,0]
	v_pk_mul_f32 v[148:149], v[148:149], v[152:153]
	v_pk_mul_f32 v[146:147], v[150:151], v[146:147]
	v_pk_mul_f32 v[150:151], v[72:73], v[178:179] op_sel_hi:[1,0]
	v_cvt_pk_bf16_f32 v146, v146, v147
	v_pk_mul_f32 v[148:149], v[150:151], v[148:149]
	s_nop 0
	v_cvt_pk_bf16_f32 v147, v148, v149
	v_mov_b64_e32 v[148:149], s[42:43]
	v_mad_i64_i32 v[148:149], s[20:21], v186, s47, v[148:149]
	v_lshl_add_u64 v[220:221], v[168:169], 1, v[148:149]
	global_store_dwordx2 v[220:221], v[146:147], off
	s_and_saveexec_b64 s[88:89], s[8:9]
	s_cbranch_execz .LBB0_920
	v_mov_b64_e32 v[146:147], s[66:67]
	v_mad_i64_i32 v[146:147], s[20:21], v177, s48, v[146:147]
	v_lshl_add_u64 v[146:147], v[168:169], 2, v[146:147]
	global_store_dwordx4 v[146:147], v[154:157], off

; __device__ __forceinline__ unsigned cvt_pk_bf16(float lo, float hi) { f32x2_t v = {lo, hi}; bf16x2_t b = __builtin_convertvector(v, bf16x2_t); return __builtin_bit_cast(unsigned, b); }
; __device__ __forceinline__ float sigm(float x) { return __builtin_amdgcn_rcpf(1.0f + __builtin_amdgcn_exp2f(-x * LOG2E)); }
;     __device__ __forceinline__ void operator()(const f32x4 (&acc)[2][2][4][2], const Unit& u, int wr, int wc, int fr, int fq) const {
;     ...
;                         const int row = row0 + ai * HALF + m * 16, rl = row - MPR, bs = rl >> 2, t = rl & 3;
;                         const f32x4 a = acc[ai][0][m][n] * rs[ai][m], uu = acc[ai][1][m][n] * rs[ai][m]; f32x4 gg, s0 = {0.f, 0.f, 0.f, 0.f}, s1 = {0.f, 0.f, 0.f, 0.f};
;                         const float* sc = sconv + (size_t)bs * 2 * 2816 + colt + 4 * n;
;                         if (t == 0) s0 = *(const f32x4*)sc;
;                         if (t <= 1) s1 = *(const f32x4*)(sc + 2816);
; #pragma unroll
;                         for (int j = 0; j < 4; ++j) {
;                             const float up1 = __shfl_up(a[j], 1, 16), up2 = __shfl_up(a[j], 2, 16);
;                             const float p1 = t == 0 ? s1[j] : up1, p2 = t == 0 ? s0[j] : (t == 1 ? s1[j] : up2);
;                             const float c = bb[j] + w0[j] * p2 + w1[j] * p1 + w2[j] * a[j];
;                             gg[j] = c * sigm(c) * uu[j];
;                         }
;                         *(u32x2*)(G + (size_t)row * 2816 + colt + 4 * n) = (u32x2){cvt_pk_bf16(gg[0], gg[1]), cvt_pk_bf16(gg[2], gg[3])};
;                         if (t >= 2) *(f32x4*)(ocs + (size_t)(bs * 2 + t - 2) * 2816 + colt + 4 * n) = a;
.LBB0_924:
	s_or_b64 exec, exec, s[88:89]
	v_pk_mul_f32 v[154:155], v[62:63], v[176:177] op_sel_hi:[1,0]
	v_mov_b32_e32 v156, v155
	s_nop 0
	v_mov_b32_dpp v156, v155 row_shr:1 row_mask:0xf bank_mask:0xf
	v_mov_b32_e32 v183, v154
	v_mov_b32_dpp v183, v154 row_shr:1 row_mask:0xf bank_mask:0xf
	v_mov_b32_e32 v185, v154
	v_mov_b32_dpp v185, v154 row_shr:2 row_mask:0xf bank_mask:0xf
	v_mov_b32_e32 v208, v155
	v_mov_b32_dpp v208, v155 row_shr:2 row_mask:0xf bank_mask:0xf
	v_lshl_add_u32 v243, v181, 1, v179
	s_waitcnt vmcnt(0) lgkmcnt(3)
	v_cndmask_b32_e64 v157, v156, v151, s[6:7]
	s_waitcnt lgkmcnt(2)
	v_cndmask_b32_e64 v156, v183, v150, s[6:7]
	s_waitcnt lgkmcnt(1)
	v_cndmask_b32_e64 v150, v185, v150, s[10:11]
	s_waitcnt lgkmcnt(0)
	v_cndmask_b32_e64 v151, v208, v151, s[10:11]
	v_cndmask_b32_e64 v147, v151, v147, s[6:7]
	v_cndmask_b32_e64 v146, v150, v146, s[6:7]
	v_pk_fma_f32 v[146:147], v[130:131], v[146:147], v[142:143]
	s_nop 0
	v_pk_fma_f32 v[146:147], v[134:135], v[156:157], v[146:147]
	v_pk_mul_f32 v[156:157], v[64:65], v[176:177] op_sel_hi:[1,0]
	v_mov_b32_e32 v183, v157
	s_nop 0
	v_mov_b32_dpp v183, v157 row_shr:1 row_mask:0xf bank_mask:0xf
	v_mov_b32_e32 v185, v156
	v_mov_b32_dpp v185, v156 row_shr:1 row_mask:0xf bank_mask:0xf
	v_mov_b32_e32 v210, v156
	v_mov_b32_dpp v210, v156 row_shr:2 row_mask:0xf bank_mask:0xf
	v_mov_b32_e32 v211, v157
	v_mov_b32_dpp v211, v157 row_shr:2 row_mask:0xf bank_mask:0xf
	v_pk_fma_f32 v[146:147], v[154:155], v[138:139], v[146:147]
	s_waitcnt lgkmcnt(3)
	v_cndmask_b32_e64 v209, v183, v153, s[6:7]
	s_waitcnt lgkmcnt(2)
	v_cndmask_b32_e64 v208, v185, v152, s[6:7]
	s_waitcnt lgkmcnt(1)
	v_cndmask_b32_e64 v152, v210, v152, s[10:11]
	s_waitcnt lgkmcnt(0)
	v_cndmask_b32_e64 v153, v211, v153, s[10:11]
	v_cndmask_b32_e64 v149, v153, v149, s[6:7]
	v_cndmask_b32_e64 v148, v152, v148, s[6:7]
	v_pk_fma_f32 v[148:149], v[132:133], v[148:149], v[144:145]
	v_mul_f32_e32 v150, 0xbfb8aa3b, v146
	v_pk_fma_f32 v[148:149], v[136:137], v[208:209], v[148:149]
	v_mul_f32_e32 v151, 0xbfb8aa3b, v147
	v_pk_fma_f32 v[148:149], v[156:157], v[140:141], v[148:149]
	v_exp_f32_e32 v150, v150
	v_exp_f32_e32 v151, v151
	v_mul_f32_e32 v152, 0xbfb8aa3b, v148
	v_mul_f32_e32 v153, 0xbfb8aa3b, v149
	v_exp_f32_e32 v152, v152
	v_exp_f32_e32 v153, v153
	v_add_f32_e32 v150, 1.0, v150
	v_add_f32_e32 v151, 1.0, v151
	v_rcp_f32_e32 v150, v150
	v_rcp_f32_e32 v151, v151
	v_add_f32_e32 v152, 1.0, v152
	v_add_f32_e32 v153, 1.0, v153
	v_rcp_f32_e32 v152, v152
	v_rcp_f32_e32 v153, v153
	v_pk_mul_f32 v[146:147], v[146:147], v[150:151]
	v_pk_mul_f32 v[150:151], v[30:31], v[176:177] op_sel_hi:[1,0]
	v_pk_mul_f32 v[148:149], v[148:149], v[152:153]
	v_pk_mul_f32 v[146:147], v[150:151], v[146:147]
	v_pk_mul_f32 v[150:151], v[32:33], v[176:177] op_sel_hi:[1,0]
	v_cvt_pk_bf16_f32 v146, v146, v147
	v_pk_mul_f32 v[148:149], v[150:151], v[148:149]
	s_nop 0
	v_cvt_pk_bf16_f32 v147, v148, v149
	v_mov_b64_e32 v[148:149], s[42:43]
	v_mad_i64_i32 v[148:149], s[20:21], v189, s47, v[148:149]
	v_lshl_add_u64 v[222:223], v[168:169], 1, v[148:149]
	global_store_dwordx2 v[222:223], v[146:147], off
	s_and_saveexec_b64 s[88:89], s[8:9]
	s_cbranch_execz .LBB0_926
	v_mov_b64_e32 v[146:147], s[66:67]
	v_mad_i64_i32 v[146:147], s[20:21], v243, s48, v[146:147]
	v_lshl_add_u64 v[146:147], v[168:169], 2, v[146:147]
	global_store_dwordx4 v[146:147], v[154:157], off

; __device__ __forceinline__ unsigned cvt_pk_bf16(float lo, float hi) { f32x2_t v = {lo, hi}; bf16x2_t b = __builtin_convertvector(v, bf16x2_t); return __builtin_bit_cast(unsigned, b); }
; __device__ __forceinline__ float sigm(float x) { return __builtin_amdgcn_rcpf(1.0f + __builtin_amdgcn_exp2f(-x * LOG2E)); }
;     __device__ __forceinline__ void operator()(const f32x4 (&acc)[2][2][4][2], const Unit& u, int wr, int wc, int fr, int fq) const {
;     ...
;                         const int row = row0 + ai * HALF + m * 16, rl = row - MPR, bs = rl >> 2, t = rl & 3;
;                         const f32x4 a = acc[ai][0][m][n] * rs[ai][m], uu = acc[ai][1][m][n] * rs[ai][m]; f32x4 gg, s0 = {0.f, 0.f, 0.f, 0.f}, s1 = {0.f, 0.f, 0.f, 0.f};
;                         const float* sc = sconv + (size_t)bs * 2 * 2816 + colt + 4 * n;
;                         if (t == 0) s0 = *(const f32x4*)sc;
;                         if (t <= 1) s1 = *(const f32x4*)(sc + 2816);
; #pragma unroll
;                         for (int j = 0; j < 4; ++j) {
;                             const float up1 = __shfl_up(a[j], 1, 16), up2 = __shfl_up(a[j], 2, 16);
;                             const float p1 = t == 0 ? s1[j] : up1, p2 = t == 0 ? s0[j] : (t == 1 ? s1[j] : up2);
;                             const float c = bb[j] + w0[j] * p2 + w1[j] * p1 + w2[j] * a[j];
;                             gg[j] = c * sigm(c) * uu[j];
;                         }
;                         *(u32x2*)(G + (size_t)row * 2816 + colt + 4 * n) = (u32x2){cvt_pk_bf16(gg[0], gg[1]), cvt_pk_bf16(gg[2], gg[3])};
;                         if (t >= 2) *(f32x4*)(ocs + (size_t)(bs * 2 + t - 2) * 2816 + colt + 4 * n) = a;
.LBB0_930:
	s_or_b64 exec, exec, s[88:89]
	v_pk_mul_f32 v[154:155], v[54:55], v[174:175] op_sel_hi:[1,0]
	v_mov_b32_e32 v156, v155
	s_nop 0
	v_mov_b32_dpp v156, v155 row_shr:1 row_mask:0xf bank_mask:0xf
	v_mov_b32_e32 v183, v154
	v_mov_b32_dpp v183, v154 row_shr:1 row_mask:0xf bank_mask:0xf
	v_mov_b32_e32 v185, v154
	v_mov_b32_dpp v185, v154 row_shr:2 row_mask:0xf bank_mask:0xf
	v_mov_b32_e32 v210, v155
	v_mov_b32_dpp v210, v155 row_shr:2 row_mask:0xf bank_mask:0xf
	v_lshl_add_u32 v244, v181, 1, v179
	s_waitcnt vmcnt(0) lgkmcnt(3)
	v_cndmask_b32_e64 v157, v156, v151, s[6:7]
	s_waitcnt lgkmcnt(2)
	v_cndmask_b32_e64 v156, v183, v150, s[6:7]
	s_waitcnt lgkmcnt(1)
	v_cndmask_b32_e64 v150, v185, v150, s[10:11]
	s_waitcnt lgkmcnt(0)
	v_cndmask_b32_e64 v151, v210, v151, s[10:11]
	v_cndmask_b32_e64 v147, v151, v147, s[6:7]
	v_cndmask_b32_e64 v146, v150, v146, s[6:7]
	v_pk_fma_f32 v[146:147], v[130:131], v[146:147], v[142:143]
	s_nop 0
	v_pk_fma_f32 v[146:147], v[134:135], v[156:157], v[146:147]
	v_pk_mul_f32 v[156:157], v[56:57], v[174:175] op_sel_hi:[1,0]
	v_mov_b32_e32 v183, v157
	s_nop 0
	v_mov_b32_dpp v183, v157 row_shr:1 row_mask:0xf bank_mask:0xf
	v_mov_b32_e32 v185, v156
	v_mov_b32_dpp v185, v156 row_shr:1 row_mask:0xf bank_mask:0xf
	v_mov_b32_e32 v212, v156
	v_mov_b32_dpp v212, v156 row_shr:2 row_mask:0xf bank_mask:0xf
	v_mov_b32_e32 v213, v157
	v_mov_b32_dpp v213, v157 row_shr:2 row_mask:0xf bank_mask:0xf
	v_pk_fma_f32 v[146:147], v[154:155], v[138:139], v[146:147]
	s_waitcnt lgkmcnt(3)
	v_cndmask_b32_e64 v211, v183, v153, s[6:7]
	s_waitcnt lgkmcnt(2)
	v_cndmask_b32_e64 v210, v185, v152, s[6:7]
	s_waitcnt lgkmcnt(1)
	v_cndmask_b32_e64 v152, v212, v152, s[10:11]
	s_waitcnt lgkmcnt(0)
	v_cndmask_b32_e64 v153, v213, v153, s[10:11]
	v_cndmask_b32_e64 v149, v153, v149, s[6:7]
	v_cndmask_b32_e64 v148, v152, v148, s[6:7]
	v_pk_fma_f32 v[148:149], v[132:133], v[148:149], v[144:145]
	v_mul_f32_e32 v150, 0xbfb8aa3b, v146
	v_pk_fma_f32 v[148:149], v[136:137], v[210:211], v[148:149]
	v_mul_f32_e32 v151, 0xbfb8aa3b, v147
	v_pk_fma_f32 v[148:149], v[156:157], v[140:141], v[148:149]
	v_exp_f32_e32 v150, v150
	v_exp_f32_e32 v151, v151
	v_mul_f32_e32 v152, 0xbfb8aa3b, v148
	v_mul_f32_e32 v153, 0xbfb8aa3b, v149
	v_exp_f32_e32 v152, v152
	v_exp_f32_e32 v153, v153
	v_add_f32_e32 v150, 1.0, v150
	v_add_f32_e32 v151, 1.0, v151
	v_rcp_f32_e32 v150, v150
	v_rcp_f32_e32 v151, v151
	v_add_f32_e32 v152, 1.0, v152
	v_add_f32_e32 v153, 1.0, v153
	v_rcp_f32_e32 v152, v152
	v_rcp_f32_e32 v153, v153
	v_pk_mul_f32 v[146:147], v[146:147], v[150:151]
	v_pk_mul_f32 v[150:151], v[22:23], v[174:175] op_sel_hi:[1,0]
	v_pk_mul_f32 v[148:149], v[148:149], v[152:153]
	v_pk_mul_f32 v[146:147], v[150:151], v[146:147]
	v_pk_mul_f32 v[150:151], v[24:25], v[174:175] op_sel_hi:[1,0]
	v_cvt_pk_bf16_f32 v146, v146, v147
	v_pk_mul_f32 v[148:149], v[150:151], v[148:149]
	s_nop 0
	v_cvt_pk_bf16_f32 v147, v148, v149
	v_mov_b64_e32 v[148:149], s[42:43]
	v_mad_i64_i32 v[148:149], s[20:21], v191, s47, v[148:149]
	v_lshl_add_u64 v[224:225], v[168:169], 1, v[148:149]
	global_store_dwordx2 v[224:225], v[146:147], off
	s_and_saveexec_b64 s[88:89], s[8:9]
	s_cbranch_execz .LBB0_932
	v_mov_b64_e32 v[146:147], s[66:67]
	v_mad_i64_i32 v[146:147], s[20:21], v244, s48, v[146:147]
	v_lshl_add_u64 v[146:147], v[168:169], 2, v[146:147]
	global_store_dwordx4 v[146:147], v[154:157], off

; __device__ __forceinline__ unsigned cvt_pk_bf16(float lo, float hi) { f32x2_t v = {lo, hi}; bf16x2_t b = __builtin_convertvector(v, bf16x2_t); return __builtin_bit_cast(unsigned, b); }
; __device__ __forceinline__ float sigm(float x) { return __builtin_amdgcn_rcpf(1.0f + __builtin_amdgcn_exp2f(-x * LOG2E)); }
;     __device__ __forceinline__ void operator()(const f32x4 (&acc)[2][2][4][2], const Unit& u, int wr, int wc, int fr, int fq) const {
;     ...
;                         const int row = row0 + ai * HALF + m * 16, rl = row - MPR, bs = rl >> 2, t = rl & 3;
;                         const f32x4 a = acc[ai][0][m][n] * rs[ai][m], uu = acc[ai][1][m][n] * rs[ai][m]; f32x4 gg, s0 = {0.f, 0.f, 0.f, 0.f}, s1 = {0.f, 0.f, 0.f, 0.f};
;                         const float* sc = sconv + (size_t)bs * 2 * 2816 + colt + 4 * n;
;                         if (t == 0) s0 = *(const f32x4*)sc;
;                         if (t <= 1) s1 = *(const f32x4*)(sc + 2816);
; #pragma unroll
;                         for (int j = 0; j < 4; ++j) {
;                             const float up1 = __shfl_up(a[j], 1, 16), up2 = __shfl_up(a[j], 2, 16);
;                             const float p1 = t == 0 ? s1[j] : up1, p2 = t == 0 ? s0[j] : (t == 1 ? s1[j] : up2);
;                             const float c = bb[j] + w0[j] * p2 + w1[j] * p1 + w2[j] * a[j];
;                             gg[j] = c * sigm(c) * uu[j];
;                         }
;                         *(u32x2*)(G + (size_t)row * 2816 + colt + 4 * n) = (u32x2){cvt_pk_bf16(gg[0], gg[1]), cvt_pk_bf16(gg[2], gg[3])};
;                         if (t >= 2) *(f32x4*)(ocs + (size_t)(bs * 2 + t - 2) * 2816 + colt + 4 * n) = a;
.LBB0_936:
	s_or_b64 exec, exec, s[88:89]
	v_pk_mul_f32 v[154:155], v[46:47], v[172:173] op_sel_hi:[1,0]
	v_mov_b32_e32 v156, v155
	s_nop 0
	v_mov_b32_dpp v156, v155 row_shr:1 row_mask:0xf bank_mask:0xf
	v_mov_b32_e32 v183, v154
	v_mov_b32_dpp v183, v154 row_shr:1 row_mask:0xf bank_mask:0xf
	v_mov_b32_e32 v185, v154
	v_mov_b32_dpp v185, v154 row_shr:2 row_mask:0xf bank_mask:0xf
	v_mov_b32_e32 v212, v155
	v_mov_b32_dpp v212, v155 row_shr:2 row_mask:0xf bank_mask:0xf
	v_lshl_add_u32 v245, v181, 1, v179
	s_waitcnt vmcnt(0) lgkmcnt(3)
	v_cndmask_b32_e64 v157, v156, v151, s[6:7]
	s_waitcnt lgkmcnt(2)
	v_cndmask_b32_e64 v156, v183, v150, s[6:7]
	s_waitcnt lgkmcnt(1)
	v_cndmask_b32_e64 v150, v185, v150, s[10:11]
	s_waitcnt lgkmcnt(0)
	v_cndmask_b32_e64 v151, v212, v151, s[10:11]
	v_cndmask_b32_e64 v147, v151, v147, s[6:7]
	v_cndmask_b32_e64 v146, v150, v146, s[6:7]
	v_pk_fma_f32 v[146:147], v[130:131], v[146:147], v[142:143]
	s_nop 0
	v_pk_fma_f32 v[146:147], v[134:135], v[156:157], v[146:147]
	v_pk_mul_f32 v[156:157], v[48:49], v[172:173] op_sel_hi:[1,0]
	v_mov_b32_e32 v183, v157
	s_nop 0
	v_mov_b32_dpp v183, v157 row_shr:1 row_mask:0xf bank_mask:0xf
	v_mov_b32_e32 v185, v156
	v_mov_b32_dpp v185, v156 row_shr:1 row_mask:0xf bank_mask:0xf
	v_mov_b32_e32 v226, v156
	v_mov_b32_dpp v226, v156 row_shr:2 row_mask:0xf bank_mask:0xf
	v_mov_b32_e32 v227, v157
	v_mov_b32_dpp v227, v157 row_shr:2 row_mask:0xf bank_mask:0xf
	v_pk_fma_f32 v[146:147], v[154:155], v[138:139], v[146:147]
	s_waitcnt lgkmcnt(3)
	v_cndmask_b32_e64 v213, v183, v153, s[6:7]
	s_waitcnt lgkmcnt(2)
	v_cndmask_b32_e64 v212, v185, v152, s[6:7]
	s_waitcnt lgkmcnt(1)
	v_cndmask_b32_e64 v152, v226, v152, s[10:11]
	s_waitcnt lgkmcnt(0)
	v_cndmask_b32_e64 v153, v227, v153, s[10:11]
	v_cndmask_b32_e64 v149, v153, v149, s[6:7]
	v_cndmask_b32_e64 v148, v152, v148, s[6:7]
	v_pk_fma_f32 v[148:149], v[132:133], v[148:149], v[144:145]
	v_mul_f32_e32 v150, 0xbfb8aa3b, v146
	v_pk_fma_f32 v[148:149], v[136:137], v[212:213], v[148:149]
	v_mul_f32_e32 v151, 0xbfb8aa3b, v147
	v_pk_fma_f32 v[148:149], v[156:157], v[140:141], v[148:149]
	v_exp_f32_e32 v150, v150
	v_exp_f32_e32 v151, v151
	v_mul_f32_e32 v152, 0xbfb8aa3b, v148
	v_mul_f32_e32 v153, 0xbfb8aa3b, v149
	v_exp_f32_e32 v152, v152
	v_exp_f32_e32 v153, v153
	v_add_f32_e32 v150, 1.0, v150
	v_add_f32_e32 v151, 1.0, v151
	v_rcp_f32_e32 v150, v150
	v_rcp_f32_e32 v151, v151
	v_add_f32_e32 v152, 1.0, v152
	v_add_f32_e32 v153, 1.0, v153
	v_rcp_f32_e32 v152, v152
	v_rcp_f32_e32 v153, v153
	v_pk_mul_f32 v[146:147], v[146:147], v[150:151]
	v_pk_mul_f32 v[150:151], v[14:15], v[172:173] op_sel_hi:[1,0]
	v_pk_mul_f32 v[148:149], v[148:149], v[152:153]
	v_pk_mul_f32 v[146:147], v[150:151], v[146:147]
	v_pk_mul_f32 v[150:151], v[16:17], v[172:173] op_sel_hi:[1,0]
	v_cvt_pk_bf16_f32 v146, v146, v147
	v_pk_mul_f32 v[148:149], v[150:151], v[148:149]
	s_nop 0
	v_cvt_pk_bf16_f32 v147, v148, v149
	v_mov_b64_e32 v[148:149], s[42:43]
	v_mad_i64_i32 v[148:149], s[20:21], v193, s47, v[148:149]
	v_lshl_add_u64 v[226:227], v[168:169], 1, v[148:149]
	global_store_dwordx2 v[226:227], v[146:147], off
	s_and_saveexec_b64 s[88:89], s[8:9]
	s_cbranch_execz .LBB0_938
	v_mov_b64_e32 v[146:147], s[66:67]
	v_mad_i64_i32 v[146:147], s[20:21], v245, s48, v[146:147]
	v_lshl_add_u64 v[146:147], v[168:169], 2, v[146:147]
	global_store_dwordx4 v[146:147], v[154:157], off

; __device__ __forceinline__ unsigned cvt_pk_bf16(float lo, float hi) { f32x2_t v = {lo, hi}; bf16x2_t b = __builtin_convertvector(v, bf16x2_t); return __builtin_bit_cast(unsigned, b); }
; __device__ __forceinline__ float sigm(float x) { return __builtin_amdgcn_rcpf(1.0f + __builtin_amdgcn_exp2f(-x * LOG2E)); }
;     __device__ __forceinline__ void operator()(const f32x4 (&acc)[2][2][4][2], const Unit& u, int wr, int wc, int fr, int fq) const {
;     ...
;                         const int row = row0 + ai * HALF + m * 16, rl = row - MPR, bs = rl >> 2, t = rl & 3;
;                         const f32x4 a = acc[ai][0][m][n] * rs[ai][m], uu = acc[ai][1][m][n] * rs[ai][m]; f32x4 gg, s0 = {0.f, 0.f, 0.f, 0.f}, s1 = {0.f, 0.f, 0.f, 0.f};
;                         const float* sc = sconv + (size_t)bs * 2 * 2816 + colt + 4 * n;
;                         if (t == 0) s0 = *(const f32x4*)sc;
;                         if (t <= 1) s1 = *(const f32x4*)(sc + 2816);
; #pragma unroll
;                         for (int j = 0; j < 4; ++j) {
;                             const float up1 = __shfl_up(a[j], 1, 16), up2 = __shfl_up(a[j], 2, 16);
;                             const float p1 = t == 0 ? s1[j] : up1, p2 = t == 0 ? s0[j] : (t == 1 ? s1[j] : up2);
;                             const float c = bb[j] + w0[j] * p2 + w1[j] * p1 + w2[j] * a[j];
;                             gg[j] = c * sigm(c) * uu[j];
;                         }
;                         *(u32x2*)(G + (size_t)row * 2816 + colt + 4 * n) = (u32x2){cvt_pk_bf16(gg[0], gg[1]), cvt_pk_bf16(gg[2], gg[3])};
;                         if (t >= 2) *(f32x4*)(ocs + (size_t)(bs * 2 + t - 2) * 2816 + colt + 4 * n) = a;
.LBB0_942:
	s_or_b64 exec, exec, s[88:89]
	v_pk_mul_f32 v[154:155], v[38:39], v[170:171] op_sel_hi:[1,0]
	v_mov_b32_e32 v156, v155
	s_nop 0
	v_mov_b32_dpp v156, v155 row_shr:1 row_mask:0xf bank_mask:0xf
	v_mov_b32_e32 v183, v154
	v_mov_b32_dpp v183, v154 row_shr:1 row_mask:0xf bank_mask:0xf
	v_mov_b32_e32 v185, v154
	v_mov_b32_dpp v185, v154 row_shr:2 row_mask:0xf bank_mask:0xf
	v_mov_b32_e32 v228, v155
	v_mov_b32_dpp v228, v155 row_shr:2 row_mask:0xf bank_mask:0xf
	v_lshl_add_u32 v242, v181, 1, v179
	s_waitcnt vmcnt(0) lgkmcnt(3)
	v_cndmask_b32_e64 v157, v156, v151, s[6:7]
	s_waitcnt lgkmcnt(2)
	v_cndmask_b32_e64 v156, v183, v150, s[6:7]
	s_waitcnt lgkmcnt(1)
	v_cndmask_b32_e64 v150, v185, v150, s[10:11]
	s_waitcnt lgkmcnt(0)
	v_cndmask_b32_e64 v151, v228, v151, s[10:11]
	v_cndmask_b32_e64 v147, v151, v147, s[6:7]
	v_cndmask_b32_e64 v146, v150, v146, s[6:7]
	v_pk_fma_f32 v[130:131], v[130:131], v[146:147], v[142:143]
	s_nop 0
	v_pk_fma_f32 v[130:131], v[134:135], v[156:157], v[130:131]
	v_pk_mul_f32 v[156:157], v[40:41], v[170:171] op_sel_hi:[1,0]
	v_pk_fma_f32 v[130:131], v[154:155], v[138:139], v[130:131]
	v_mov_b32_e32 v138, v157
	s_nop 0
	v_mov_b32_dpp v138, v157 row_shr:1 row_mask:0xf bank_mask:0xf
	v_mov_b32_e32 v142, v156
	v_mov_b32_dpp v142, v156 row_shr:1 row_mask:0xf bank_mask:0xf
	v_mov_b32_e32 v143, v156
	v_mov_b32_dpp v143, v156 row_shr:2 row_mask:0xf bank_mask:0xf
	v_mov_b32_e32 v146, v157
	v_mov_b32_dpp v146, v157 row_shr:2 row_mask:0xf bank_mask:0xf
	v_mul_f32_e32 v134, 0xbfb8aa3b, v130
	s_waitcnt lgkmcnt(3)
	v_cndmask_b32_e64 v139, v138, v153, s[6:7]
	s_waitcnt lgkmcnt(2)
	v_cndmask_b32_e64 v138, v142, v152, s[6:7]
	s_waitcnt lgkmcnt(1)
	v_cndmask_b32_e64 v142, v143, v152, s[10:11]
	s_waitcnt lgkmcnt(0)
	v_cndmask_b32_e64 v143, v146, v153, s[10:11]
	v_cndmask_b32_e64 v143, v143, v149, s[6:7]
	v_cndmask_b32_e64 v142, v142, v148, s[6:7]
	v_pk_fma_f32 v[132:133], v[132:133], v[142:143], v[144:145]
	v_mul_f32_e32 v135, 0xbfb8aa3b, v131
	v_pk_fma_f32 v[132:133], v[136:137], v[138:139], v[132:133]
	v_exp_f32_e32 v134, v134
	v_pk_fma_f32 v[132:133], v[156:157], v[140:141], v[132:133]
	v_exp_f32_e32 v135, v135
	v_mul_f32_e32 v136, 0xbfb8aa3b, v132
	v_mul_f32_e32 v137, 0xbfb8aa3b, v133
	v_exp_f32_e32 v136, v136
	v_exp_f32_e32 v137, v137
	v_add_f32_e32 v134, 1.0, v134
	v_add_f32_e32 v135, 1.0, v135
	v_rcp_f32_e32 v134, v134
	v_rcp_f32_e32 v135, v135
	v_add_f32_e32 v136, 1.0, v136
	v_add_f32_e32 v137, 1.0, v137
	v_rcp_f32_e32 v136, v136
	v_rcp_f32_e32 v137, v137
	v_pk_mul_f32 v[130:131], v[130:131], v[134:135]
	v_pk_mul_f32 v[134:135], v[6:7], v[170:171] op_sel_hi:[1,0]
	v_pk_mul_f32 v[132:133], v[132:133], v[136:137]
	v_pk_mul_f32 v[130:131], v[134:135], v[130:131]
	v_pk_mul_f32 v[134:135], v[8:9], v[170:171] op_sel_hi:[1,0]
	v_cvt_pk_bf16_f32 v130, v130, v131
	v_pk_mul_f32 v[132:133], v[134:135], v[132:133]
	s_nop 0
	v_cvt_pk_bf16_f32 v131, v132, v133
	v_mov_b64_e32 v[132:133], s[42:43]
	v_mad_i64_i32 v[132:133], s[20:21], v187, s47, v[132:133]
	v_lshl_add_u64 v[228:229], v[168:169], 1, v[132:133]
	global_store_dwordx2 v[228:229], v[130:131], off
	s_and_saveexec_b64 s[88:89], s[8:9]
	s_cbranch_execz .LBB0_944
	v_lshl_add_u32 v132, v181, 1, v179
	v_mov_b64_e32 v[130:131], s[66:67]
	v_mad_i64_i32 v[130:131], s[20:21], v132, s48, v[130:131]
	v_lshl_add_u64 v[130:131], v[168:169], 2, v[130:131]
	global_store_dwordx4 v[130:131], v[154:157], off

; __device__ __forceinline__ unsigned cvt_pk_bf16(float lo, float hi) { f32x2_t v = {lo, hi}; bf16x2_t b = __builtin_convertvector(v, bf16x2_t); return __builtin_bit_cast(unsigned, b); }
; __device__ __forceinline__ float sigm(float x) { return __builtin_amdgcn_rcpf(1.0f + __builtin_amdgcn_exp2f(-x * LOG2E)); }
;     __device__ __forceinline__ void operator()(const f32x4 (&acc)[2][2][4][2], const Unit& u, int wr, int wc, int fr, int fq) const {
;     ...
;                         const int row = row0 + ai * HALF + m * 16, rl = row - MPR, bs = rl >> 2, t = rl & 3;
;                         const f32x4 a = acc[ai][0][m][n] * rs[ai][m], uu = acc[ai][1][m][n] * rs[ai][m]; f32x4 gg, s0 = {0.f, 0.f, 0.f, 0.f}, s1 = {0.f, 0.f, 0.f, 0.f};
;                         const float* sc = sconv + (size_t)bs * 2 * 2816 + colt + 4 * n;
;                         if (t == 0) s0 = *(const f32x4*)sc;
;                         if (t <= 1) s1 = *(const f32x4*)(sc + 2816);
; #pragma unroll
;                         for (int j = 0; j < 4; ++j) {
;                             const float up1 = __shfl_up(a[j], 1, 16), up2 = __shfl_up(a[j], 2, 16);
;                             const float p1 = t == 0 ? s1[j] : up1, p2 = t == 0 ? s0[j] : (t == 1 ? s1[j] : up2);
;                             const float c = bb[j] + w0[j] * p2 + w1[j] * p1 + w2[j] * a[j];
;                             gg[j] = c * sigm(c) * uu[j];
;                         }
;                         *(u32x2*)(G + (size_t)row * 2816 + colt + 4 * n) = (u32x2){cvt_pk_bf16(gg[0], gg[1]), cvt_pk_bf16(gg[2], gg[3])};
;                         if (t >= 2) *(f32x4*)(ocs + (size_t)(bs * 2 + t - 2) * 2816 + colt + 4 * n) = a;
.LBB0_948:
	s_or_b64 exec, exec, s[88:89]
	v_mov_b32_e32 v185, v184
	v_pk_mul_f32 v[154:155], v[122:123], v[184:185]
	v_mov_b32_e32 v156, v155
	s_nop 0
	v_mov_b32_dpp v156, v155 row_shr:1 row_mask:0xf bank_mask:0xf
	v_mov_b32_e32 v179, v154
	v_mov_b32_dpp v179, v154 row_shr:1 row_mask:0xf bank_mask:0xf
	v_mov_b32_e32 v181, v154
	v_mov_b32_dpp v181, v154 row_shr:2 row_mask:0xf bank_mask:0xf
	v_mov_b32_e32 v183, v155
	v_mov_b32_dpp v183, v155 row_shr:2 row_mask:0xf bank_mask:0xf
	s_waitcnt vmcnt(0) lgkmcnt(3)
	v_cndmask_b32_e64 v157, v156, v151, s[6:7]
	s_waitcnt lgkmcnt(2)
	v_cndmask_b32_e64 v156, v179, v150, s[6:7]
	s_waitcnt lgkmcnt(1)
	v_cndmask_b32_e64 v150, v181, v150, s[10:11]
	s_waitcnt lgkmcnt(0)
	v_cndmask_b32_e64 v151, v183, v151, s[10:11]
	v_cndmask_b32_e64 v147, v151, v147, s[6:7]
	v_cndmask_b32_e64 v146, v150, v146, s[6:7]
	v_pk_fma_f32 v[146:147], v[130:131], v[146:147], v[142:143]
	v_mov_b32_e32 v151, v184
	v_pk_fma_f32 v[146:147], v[134:135], v[156:157], v[146:147]
	s_nop 0
	v_pk_fma_f32 v[146:147], v[154:155], v[138:139], v[146:147]
	s_nop 0
	v_mul_f32_e32 v150, 0xbfb8aa3b, v146
	v_exp_f32_e32 v179, v150
	v_mov_b32_e32 v150, v184
	v_pk_mul_f32 v[156:157], v[124:125], v[150:151]
	v_mov_b32_e32 v181, v157
	s_nop 0
	v_mov_b32_dpp v181, v157 row_shr:1 row_mask:0xf bank_mask:0xf
	v_mov_b32_e32 v183, v156
	v_mov_b32_dpp v183, v156 row_shr:1 row_mask:0xf bank_mask:0xf
	v_mov_b32_e32 v185, v156
	v_mov_b32_dpp v185, v156 row_shr:2 row_mask:0xf bank_mask:0xf
	v_mov_b32_e32 v195, v157
	v_mov_b32_dpp v195, v157 row_shr:2 row_mask:0xf bank_mask:0xf
	v_add_f32_e32 v179, 1.0, v179
	s_waitcnt lgkmcnt(3)
	v_cndmask_b32_e64 v203, v181, v153, s[6:7]
	s_waitcnt lgkmcnt(2)
	v_cndmask_b32_e64 v202, v183, v152, s[6:7]
	s_waitcnt lgkmcnt(1)
	v_cndmask_b32_e64 v152, v185, v152, s[10:11]
	s_waitcnt lgkmcnt(0)
	v_cndmask_b32_e64 v153, v195, v153, s[10:11]
	v_cndmask_b32_e64 v149, v153, v149, s[6:7]
	v_cndmask_b32_e64 v148, v152, v148, s[6:7]
	v_pk_fma_f32 v[148:149], v[132:133], v[148:149], v[144:145]
	v_rcp_f32_e32 v194, v179
	v_pk_fma_f32 v[148:149], v[136:137], v[202:203], v[148:149]
	v_mul_f32_e32 v179, 0xbfb8aa3b, v147
	v_pk_fma_f32 v[148:149], v[156:157], v[140:141], v[148:149]
	v_exp_f32_e32 v179, v179
	v_mul_f32_e32 v152, 0xbfb8aa3b, v148
	v_mul_f32_e32 v153, 0xbfb8aa3b, v149
	v_exp_f32_e32 v152, v152
	v_exp_f32_e32 v153, v153
	v_add_f32_e32 v179, 1.0, v179
	v_rcp_f32_e32 v195, v179
	v_add_f32_e32 v152, 1.0, v152
	v_add_f32_e32 v153, 1.0, v153
	v_rcp_f32_e32 v152, v152
	v_rcp_f32_e32 v153, v153
	v_pk_mul_f32 v[146:147], v[146:147], v[194:195]
	v_pk_mul_f32 v[194:195], v[90:91], v[150:151]
	v_pk_mul_f32 v[150:151], v[92:93], v[150:151]
	v_pk_mul_f32 v[148:149], v[148:149], v[152:153]
	v_pk_mul_f32 v[146:147], v[194:195], v[146:147]
	v_pk_mul_f32 v[148:149], v[150:151], v[148:149]
	v_cvt_pk_bf16_f32 v146, v146, v147
	v_cvt_pk_bf16_f32 v147, v148, v149
	global_store_dwordx2 v[214:215], v[146:147], off offset:8
	s_and_saveexec_b64 s[88:89], s[8:9]
	s_cbranch_execz .LBB0_950
	v_mov_b64_e32 v[146:147], s[66:67]
	v_mad_i64_i32 v[146:147], s[20:21], v171, s48, v[146:147]
	v_lshl_add_u64 v[146:147], v[168:169], 2, v[146:147]
	global_store_dwordx4 v[146:147], v[154:157], off offset:16

; __device__ __forceinline__ unsigned cvt_pk_bf16(float lo, float hi) { f32x2_t v = {lo, hi}; bf16x2_t b = __builtin_convertvector(v, bf16x2_t); return __builtin_bit_cast(unsigned, b); }
; __device__ __forceinline__ float sigm(float x) { return __builtin_amdgcn_rcpf(1.0f + __builtin_amdgcn_exp2f(-x * LOG2E)); }
;     __device__ __forceinline__ void operator()(const f32x4 (&acc)[2][2][4][2], const Unit& u, int wr, int wc, int fr, int fq) const {
;     ...
;                         const int row = row0 + ai * HALF + m * 16, rl = row - MPR, bs = rl >> 2, t = rl & 3;
;                         const f32x4 a = acc[ai][0][m][n] * rs[ai][m], uu = acc[ai][1][m][n] * rs[ai][m]; f32x4 gg, s0 = {0.f, 0.f, 0.f, 0.f}, s1 = {0.f, 0.f, 0.f, 0.f};
;                         const float* sc = sconv + (size_t)bs * 2 * 2816 + colt + 4 * n;
;                         if (t == 0) s0 = *(const f32x4*)sc;
;                         if (t <= 1) s1 = *(const f32x4*)(sc + 2816);
; #pragma unroll
;                         for (int j = 0; j < 4; ++j) {
;                             const float up1 = __shfl_up(a[j], 1, 16), up2 = __shfl_up(a[j], 2, 16);
;                             const float p1 = t == 0 ? s1[j] : up1, p2 = t == 0 ? s0[j] : (t == 1 ? s1[j] : up2);
;                             const float c = bb[j] + w0[j] * p2 + w1[j] * p1 + w2[j] * a[j];
;                             gg[j] = c * sigm(c) * uu[j];
;                         }
;                         *(u32x2*)(G + (size_t)row * 2816 + colt + 4 * n) = (u32x2){cvt_pk_bf16(gg[0], gg[1]), cvt_pk_bf16(gg[2], gg[3])};
;                         if (t >= 2) *(f32x4*)(ocs + (size_t)(bs * 2 + t - 2) * 2816 + colt + 4 * n) = a;
.LBB0_954:
	s_or_b64 exec, exec, s[88:89]
	v_mov_b32_e32 v183, v182
	v_pk_mul_f32 v[154:155], v[114:115], v[182:183]
	v_mov_b32_e32 v156, v155
	s_nop 0
	v_mov_b32_dpp v156, v155 row_shr:1 row_mask:0xf bank_mask:0xf
	v_mov_b32_e32 v171, v154
	v_mov_b32_dpp v171, v154 row_shr:1 row_mask:0xf bank_mask:0xf
	v_mov_b32_e32 v179, v154
	v_mov_b32_dpp v179, v154 row_shr:2 row_mask:0xf bank_mask:0xf
	v_mov_b32_e32 v181, v155
	v_mov_b32_dpp v181, v155 row_shr:2 row_mask:0xf bank_mask:0xf
	s_waitcnt vmcnt(0) lgkmcnt(3)
	v_cndmask_b32_e64 v157, v156, v151, s[6:7]
	s_waitcnt lgkmcnt(2)
	v_cndmask_b32_e64 v156, v171, v150, s[6:7]
	s_waitcnt lgkmcnt(1)
	v_cndmask_b32_e64 v150, v179, v150, s[10:11]
	s_waitcnt lgkmcnt(0)
	v_cndmask_b32_e64 v151, v181, v151, s[10:11]
	v_cndmask_b32_e64 v147, v151, v147, s[6:7]
	v_cndmask_b32_e64 v146, v150, v146, s[6:7]
	v_pk_fma_f32 v[146:147], v[130:131], v[146:147], v[142:143]
	v_mov_b32_e32 v151, v182
	v_pk_fma_f32 v[146:147], v[134:135], v[156:157], v[146:147]
	s_nop 0
	v_pk_fma_f32 v[146:147], v[154:155], v[138:139], v[146:147]
	s_nop 0
	v_mul_f32_e32 v150, 0xbfb8aa3b, v146
	v_exp_f32_e32 v171, v150
	v_mov_b32_e32 v150, v182
	v_pk_mul_f32 v[156:157], v[116:117], v[150:151]
	v_mov_b32_e32 v179, v157
	s_nop 0
	v_mov_b32_dpp v179, v157 row_shr:1 row_mask:0xf bank_mask:0xf
	v_mov_b32_e32 v181, v156
	v_mov_b32_dpp v181, v156 row_shr:1 row_mask:0xf bank_mask:0xf
	v_mov_b32_e32 v183, v156
	v_mov_b32_dpp v183, v156 row_shr:2 row_mask:0xf bank_mask:0xf
	v_mov_b32_e32 v185, v157
	v_mov_b32_dpp v185, v157 row_shr:2 row_mask:0xf bank_mask:0xf
	v_add_f32_e32 v171, 1.0, v171
	s_waitcnt lgkmcnt(3)
	v_cndmask_b32_e64 v197, v179, v153, s[6:7]
	s_waitcnt lgkmcnt(2)
	v_cndmask_b32_e64 v196, v181, v152, s[6:7]
	s_waitcnt lgkmcnt(1)
	v_cndmask_b32_e64 v152, v183, v152, s[10:11]
	s_waitcnt lgkmcnt(0)
	v_cndmask_b32_e64 v153, v185, v153, s[10:11]
	v_cndmask_b32_e64 v149, v153, v149, s[6:7]
	v_cndmask_b32_e64 v148, v152, v148, s[6:7]
	v_pk_fma_f32 v[148:149], v[132:133], v[148:149], v[144:145]
	v_rcp_f32_e32 v194, v171
	v_pk_fma_f32 v[148:149], v[136:137], v[196:197], v[148:149]
	v_mul_f32_e32 v171, 0xbfb8aa3b, v147
	v_pk_fma_f32 v[148:149], v[156:157], v[140:141], v[148:149]
	v_exp_f32_e32 v171, v171
	v_mul_f32_e32 v152, 0xbfb8aa3b, v148
	v_mul_f32_e32 v153, 0xbfb8aa3b, v149
	v_exp_f32_e32 v152, v152
	v_exp_f32_e32 v153, v153
	v_add_f32_e32 v171, 1.0, v171
	v_rcp_f32_e32 v195, v171
	v_add_f32_e32 v152, 1.0, v152
	v_add_f32_e32 v153, 1.0, v153
	v_rcp_f32_e32 v152, v152
	v_rcp_f32_e32 v153, v153
	v_pk_mul_f32 v[146:147], v[146:147], v[194:195]
	v_pk_mul_f32 v[194:195], v[82:83], v[150:151]
	v_pk_mul_f32 v[150:151], v[84:85], v[150:151]
	v_pk_mul_f32 v[148:149], v[148:149], v[152:153]
	v_pk_mul_f32 v[146:147], v[194:195], v[146:147]
	v_pk_mul_f32 v[148:149], v[150:151], v[148:149]
	v_cvt_pk_bf16_f32 v146, v146, v147
	v_cvt_pk_bf16_f32 v147, v148, v149
	global_store_dwordx2 v[216:217], v[146:147], off offset:8
	s_and_saveexec_b64 s[88:89], s[8:9]
	s_cbranch_execz .LBB0_956
	v_mov_b64_e32 v[146:147], s[66:67]
	v_mad_i64_i32 v[146:147], s[20:21], v173, s48, v[146:147]
	v_lshl_add_u64 v[146:147], v[168:169], 2, v[146:147]
	global_store_dwordx4 v[146:147], v[154:157], off offset:16

; __device__ __forceinline__ unsigned cvt_pk_bf16(float lo, float hi) { f32x2_t v = {lo, hi}; bf16x2_t b = __builtin_convertvector(v, bf16x2_t); return __builtin_bit_cast(unsigned, b); }
; __device__ __forceinline__ float sigm(float x) { return __builtin_amdgcn_rcpf(1.0f + __builtin_amdgcn_exp2f(-x * LOG2E)); }
;     __device__ __forceinline__ void operator()(const f32x4 (&acc)[2][2][4][2], const Unit& u, int wr, int wc, int fr, int fq) const {
;     ...
;                         const int row = row0 + ai * HALF + m * 16, rl = row - MPR, bs = rl >> 2, t = rl & 3;
;                         const f32x4 a = acc[ai][0][m][n] * rs[ai][m], uu = acc[ai][1][m][n] * rs[ai][m]; f32x4 gg, s0 = {0.f, 0.f, 0.f, 0.f}, s1 = {0.f, 0.f, 0.f, 0.f};
;                         const float* sc = sconv + (size_t)bs * 2 * 2816 + colt + 4 * n;
;                         if (t == 0) s0 = *(const f32x4*)sc;
;                         if (t <= 1) s1 = *(const f32x4*)(sc + 2816);
; #pragma unroll
;                         for (int j = 0; j < 4; ++j) {
;                             const float up1 = __shfl_up(a[j], 1, 16), up2 = __shfl_up(a[j], 2, 16);
;                             const float p1 = t == 0 ? s1[j] : up1, p2 = t == 0 ? s0[j] : (t == 1 ? s1[j] : up2);
;                             const float c = bb[j] + w0[j] * p2 + w1[j] * p1 + w2[j] * a[j];
;                             gg[j] = c * sigm(c) * uu[j];
;                         }
;                         *(u32x2*)(G + (size_t)row * 2816 + colt + 4 * n) = (u32x2){cvt_pk_bf16(gg[0], gg[1]), cvt_pk_bf16(gg[2], gg[3])};
;                         if (t >= 2) *(f32x4*)(ocs + (size_t)(bs * 2 + t - 2) * 2816 + colt + 4 * n) = a;
.LBB0_960:
	s_or_b64 exec, exec, s[88:89]
	v_mov_b32_e32 v181, v180
	v_pk_mul_f32 v[154:155], v[106:107], v[180:181]
	v_mov_b32_e32 v156, v155
	s_nop 0
	v_mov_b32_dpp v156, v155 row_shr:1 row_mask:0xf bank_mask:0xf
	v_mov_b32_e32 v171, v154
	v_mov_b32_dpp v171, v154 row_shr:1 row_mask:0xf bank_mask:0xf
	v_mov_b32_e32 v173, v154
	v_mov_b32_dpp v173, v154 row_shr:2 row_mask:0xf bank_mask:0xf
	v_mov_b32_e32 v179, v155
	v_mov_b32_dpp v179, v155 row_shr:2 row_mask:0xf bank_mask:0xf
	s_waitcnt vmcnt(0) lgkmcnt(3)
	v_cndmask_b32_e64 v157, v156, v151, s[6:7]
	s_waitcnt lgkmcnt(2)
	v_cndmask_b32_e64 v156, v171, v150, s[6:7]
	s_waitcnt lgkmcnt(1)
	v_cndmask_b32_e64 v150, v173, v150, s[10:11]
	s_waitcnt lgkmcnt(0)
	v_cndmask_b32_e64 v151, v179, v151, s[10:11]
	v_cndmask_b32_e64 v147, v151, v147, s[6:7]
	v_cndmask_b32_e64 v146, v150, v146, s[6:7]
	v_pk_fma_f32 v[146:147], v[130:131], v[146:147], v[142:143]
	v_mov_b32_e32 v151, v180
	v_pk_fma_f32 v[146:147], v[134:135], v[156:157], v[146:147]
	s_nop 0
	v_pk_fma_f32 v[146:147], v[154:155], v[138:139], v[146:147]
	s_nop 0
	v_mul_f32_e32 v150, 0xbfb8aa3b, v146
	v_exp_f32_e32 v171, v150
	v_mov_b32_e32 v150, v180
	v_pk_mul_f32 v[156:157], v[108:109], v[150:151]
	v_mov_b32_e32 v173, v157
	s_nop 0
	v_mov_b32_dpp v173, v157 row_shr:1 row_mask:0xf bank_mask:0xf
	v_mov_b32_e32 v179, v156
	v_mov_b32_dpp v179, v156 row_shr:1 row_mask:0xf bank_mask:0xf
	v_mov_b32_e32 v181, v156
	v_mov_b32_dpp v181, v156 row_shr:2 row_mask:0xf bank_mask:0xf
	v_mov_b32_e32 v183, v157
	v_mov_b32_dpp v183, v157 row_shr:2 row_mask:0xf bank_mask:0xf
	v_add_f32_e32 v171, 1.0, v171
	s_waitcnt lgkmcnt(3)
	v_cndmask_b32_e64 v197, v173, v153, s[6:7]
	s_waitcnt lgkmcnt(2)
	v_cndmask_b32_e64 v196, v179, v152, s[6:7]
	s_waitcnt lgkmcnt(1)
	v_cndmask_b32_e64 v152, v181, v152, s[10:11]
	s_waitcnt lgkmcnt(0)
	v_cndmask_b32_e64 v153, v183, v153, s[10:11]
	v_cndmask_b32_e64 v149, v153, v149, s[6:7]
	v_cndmask_b32_e64 v148, v152, v148, s[6:7]
	v_pk_fma_f32 v[148:149], v[132:133], v[148:149], v[144:145]
	v_rcp_f32_e32 v194, v171
	v_pk_fma_f32 v[148:149], v[136:137], v[196:197], v[148:149]
	v_mul_f32_e32 v171, 0xbfb8aa3b, v147
	v_pk_fma_f32 v[148:149], v[156:157], v[140:141], v[148:149]
	v_exp_f32_e32 v171, v171
	v_mul_f32_e32 v152, 0xbfb8aa3b, v148
	v_mul_f32_e32 v153, 0xbfb8aa3b, v149
	v_exp_f32_e32 v152, v152
	v_exp_f32_e32 v153, v153
	v_add_f32_e32 v171, 1.0, v171
	v_rcp_f32_e32 v195, v171
	v_add_f32_e32 v152, 1.0, v152
	v_add_f32_e32 v153, 1.0, v153
	v_rcp_f32_e32 v152, v152
	v_rcp_f32_e32 v153, v153
	v_pk_mul_f32 v[146:147], v[146:147], v[194:195]
	v_pk_mul_f32 v[194:195], v[74:75], v[150:151]
	v_pk_mul_f32 v[150:151], v[76:77], v[150:151]
	v_pk_mul_f32 v[148:149], v[148:149], v[152:153]
	v_pk_mul_f32 v[146:147], v[194:195], v[146:147]
	v_pk_mul_f32 v[148:149], v[150:151], v[148:149]
	v_cvt_pk_bf16_f32 v146, v146, v147
	v_cvt_pk_bf16_f32 v147, v148, v149
	global_store_dwordx2 v[218:219], v[146:147], off offset:8
	s_and_saveexec_b64 s[88:89], s[8:9]
	s_cbranch_execz .LBB0_962
	v_mov_b64_e32 v[146:147], s[66:67]
	v_mad_i64_i32 v[146:147], s[20:21], v175, s48, v[146:147]
	v_lshl_add_u64 v[146:147], v[168:169], 2, v[146:147]
	global_store_dwordx4 v[146:147], v[154:157], off offset:16

; __device__ __forceinline__ unsigned cvt_pk_bf16(float lo, float hi) { f32x2_t v = {lo, hi}; bf16x2_t b = __builtin_convertvector(v, bf16x2_t); return __builtin_bit_cast(unsigned, b); }
; __device__ __forceinline__ float sigm(float x) { return __builtin_amdgcn_rcpf(1.0f + __builtin_amdgcn_exp2f(-x * LOG2E)); }
;     __device__ __forceinline__ void operator()(const f32x4 (&acc)[2][2][4][2], const Unit& u, int wr, int wc, int fr, int fq) const {
;     ...
;                         const int row = row0 + ai * HALF + m * 16, rl = row - MPR, bs = rl >> 2, t = rl & 3;
;                         const f32x4 a = acc[ai][0][m][n] * rs[ai][m], uu = acc[ai][1][m][n] * rs[ai][m]; f32x4 gg, s0 = {0.f, 0.f, 0.f, 0.f}, s1 = {0.f, 0.f, 0.f, 0.f};
;                         const float* sc = sconv + (size_t)bs * 2 * 2816 + colt + 4 * n;
;                         if (t == 0) s0 = *(const f32x4*)sc;
;                         if (t <= 1) s1 = *(const f32x4*)(sc + 2816);
; #pragma unroll
;                         for (int j = 0; j < 4; ++j) {
;                             const float up1 = __shfl_up(a[j], 1, 16), up2 = __shfl_up(a[j], 2, 16);
;                             const float p1 = t == 0 ? s1[j] : up1, p2 = t == 0 ? s0[j] : (t == 1 ? s1[j] : up2);
;                             const float c = bb[j] + w0[j] * p2 + w1[j] * p1 + w2[j] * a[j];
;                             gg[j] = c * sigm(c) * uu[j];
;                         }
;                         *(u32x2*)(G + (size_t)row * 2816 + colt + 4 * n) = (u32x2){cvt_pk_bf16(gg[0], gg[1]), cvt_pk_bf16(gg[2], gg[3])};
;                         if (t >= 2) *(f32x4*)(ocs + (size_t)(bs * 2 + t - 2) * 2816 + colt + 4 * n) = a;
.LBB0_966:
	s_or_b64 exec, exec, s[88:89]
	v_mov_b32_e32 v179, v178
	v_pk_mul_f32 v[154:155], v[98:99], v[178:179]
	v_mov_b32_e32 v156, v155
	s_nop 0
	v_mov_b32_dpp v156, v155 row_shr:1 row_mask:0xf bank_mask:0xf
	v_mov_b32_e32 v171, v154
	v_mov_b32_dpp v171, v154 row_shr:1 row_mask:0xf bank_mask:0xf
	v_mov_b32_e32 v173, v154
	v_mov_b32_dpp v173, v154 row_shr:2 row_mask:0xf bank_mask:0xf
	v_mov_b32_e32 v175, v155
	v_mov_b32_dpp v175, v155 row_shr:2 row_mask:0xf bank_mask:0xf
	s_waitcnt vmcnt(0) lgkmcnt(3)
	v_cndmask_b32_e64 v157, v156, v151, s[6:7]
	s_waitcnt lgkmcnt(2)
	v_cndmask_b32_e64 v156, v171, v150, s[6:7]
	s_waitcnt lgkmcnt(1)
	v_cndmask_b32_e64 v150, v173, v150, s[10:11]
	s_waitcnt lgkmcnt(0)
	v_cndmask_b32_e64 v151, v175, v151, s[10:11]
	v_cndmask_b32_e64 v147, v151, v147, s[6:7]
	v_cndmask_b32_e64 v146, v150, v146, s[6:7]
	v_pk_fma_f32 v[146:147], v[130:131], v[146:147], v[142:143]
	v_mov_b32_e32 v151, v178
	v_pk_fma_f32 v[146:147], v[134:135], v[156:157], v[146:147]
	s_nop 0
	v_pk_fma_f32 v[146:147], v[154:155], v[138:139], v[146:147]
	s_nop 0
	v_mul_f32_e32 v150, 0xbfb8aa3b, v146
	v_exp_f32_e32 v171, v150
	v_mov_b32_e32 v150, v178
	v_pk_mul_f32 v[156:157], v[100:101], v[150:151]
	v_mov_b32_e32 v173, v157
	s_nop 0
	v_mov_b32_dpp v173, v157 row_shr:1 row_mask:0xf bank_mask:0xf
	v_mov_b32_e32 v175, v156
	v_mov_b32_dpp v175, v156 row_shr:1 row_mask:0xf bank_mask:0xf
	v_mov_b32_e32 v179, v156
	v_mov_b32_dpp v179, v156 row_shr:2 row_mask:0xf bank_mask:0xf
	v_mov_b32_e32 v181, v157
	v_mov_b32_dpp v181, v157 row_shr:2 row_mask:0xf bank_mask:0xf
	v_add_f32_e32 v171, 1.0, v171
	s_waitcnt lgkmcnt(3)
	v_cndmask_b32_e64 v197, v173, v153, s[6:7]
	s_waitcnt lgkmcnt(2)
	v_cndmask_b32_e64 v196, v175, v152, s[6:7]
	s_waitcnt lgkmcnt(1)
	v_cndmask_b32_e64 v152, v179, v152, s[10:11]
	s_waitcnt lgkmcnt(0)
	v_cndmask_b32_e64 v153, v181, v153, s[10:11]
	v_cndmask_b32_e64 v149, v153, v149, s[6:7]
	v_cndmask_b32_e64 v148, v152, v148, s[6:7]
	v_pk_fma_f32 v[148:149], v[132:133], v[148:149], v[144:145]
	v_rcp_f32_e32 v194, v171
	v_pk_fma_f32 v[148:149], v[136:137], v[196:197], v[148:149]
	v_mul_f32_e32 v171, 0xbfb8aa3b, v147
	v_pk_fma_f32 v[148:149], v[156:157], v[140:141], v[148:149]
	v_exp_f32_e32 v171, v171
	v_mul_f32_e32 v152, 0xbfb8aa3b, v148
	v_mul_f32_e32 v153, 0xbfb8aa3b, v149
	v_exp_f32_e32 v152, v152
	v_exp_f32_e32 v153, v153
	v_add_f32_e32 v171, 1.0, v171
	v_rcp_f32_e32 v195, v171
	v_add_f32_e32 v152, 1.0, v152
	v_add_f32_e32 v153, 1.0, v153
	v_rcp_f32_e32 v152, v152
	v_rcp_f32_e32 v153, v153
	v_pk_mul_f32 v[146:147], v[146:147], v[194:195]
	v_pk_mul_f32 v[194:195], v[66:67], v[150:151]
	v_pk_mul_f32 v[150:151], v[68:69], v[150:151]
	v_pk_mul_f32 v[148:149], v[148:149], v[152:153]
	v_pk_mul_f32 v[146:147], v[194:195], v[146:147]
	v_pk_mul_f32 v[148:149], v[150:151], v[148:149]
	v_cvt_pk_bf16_f32 v146, v146, v147
	v_cvt_pk_bf16_f32 v147, v148, v149
	global_store_dwordx2 v[220:221], v[146:147], off offset:8
	s_and_saveexec_b64 s[88:89], s[8:9]
	s_cbranch_execz .LBB0_968
	v_mov_b64_e32 v[146:147], s[66:67]
	v_mad_i64_i32 v[146:147], s[20:21], v177, s48, v[146:147]
	v_lshl_add_u64 v[146:147], v[168:169], 2, v[146:147]
	global_store_dwordx4 v[146:147], v[154:157], off offset:16

; __device__ __forceinline__ unsigned cvt_pk_bf16(float lo, float hi) { f32x2_t v = {lo, hi}; bf16x2_t b = __builtin_convertvector(v, bf16x2_t); return __builtin_bit_cast(unsigned, b); }
; __device__ __forceinline__ float sigm(float x) { return __builtin_amdgcn_rcpf(1.0f + __builtin_amdgcn_exp2f(-x * LOG2E)); }
;     __device__ __forceinline__ void operator()(const f32x4 (&acc)[2][2][4][2], const Unit& u, int wr, int wc, int fr, int fq) const {
;     ...
;                         const int row = row0 + ai * HALF + m * 16, rl = row - MPR, bs = rl >> 2, t = rl & 3;
;                         const f32x4 a = acc[ai][0][m][n] * rs[ai][m], uu = acc[ai][1][m][n] * rs[ai][m]; f32x4 gg, s0 = {0.f, 0.f, 0.f, 0.f}, s1 = {0.f, 0.f, 0.f, 0.f};
;                         const float* sc = sconv + (size_t)bs * 2 * 2816 + colt + 4 * n;
;                         if (t == 0) s0 = *(const f32x4*)sc;
;                         if (t <= 1) s1 = *(const f32x4*)(sc + 2816);
; #pragma unroll
;                         for (int j = 0; j < 4; ++j) {
;                             const float up1 = __shfl_up(a[j], 1, 16), up2 = __shfl_up(a[j], 2, 16);
;                             const float p1 = t == 0 ? s1[j] : up1, p2 = t == 0 ? s0[j] : (t == 1 ? s1[j] : up2);
;                             const float c = bb[j] + w0[j] * p2 + w1[j] * p1 + w2[j] * a[j];
;                             gg[j] = c * sigm(c) * uu[j];
;                         }
;                         *(u32x2*)(G + (size_t)row * 2816 + colt + 4 * n) = (u32x2){cvt_pk_bf16(gg[0], gg[1]), cvt_pk_bf16(gg[2], gg[3])};
;                         if (t >= 2) *(f32x4*)(ocs + (size_t)(bs * 2 + t - 2) * 2816 + colt + 4 * n) = a;
.LBB0_972:
	s_or_b64 exec, exec, s[88:89]
	v_mov_b32_e32 v177, v176
	v_pk_mul_f32 v[154:155], v[58:59], v[176:177]
	v_mov_b32_e32 v156, v155
	s_nop 0
	v_mov_b32_dpp v156, v155 row_shr:1 row_mask:0xf bank_mask:0xf
	v_mov_b32_e32 v171, v154
	v_mov_b32_dpp v171, v154 row_shr:1 row_mask:0xf bank_mask:0xf
	v_mov_b32_e32 v173, v154
	v_mov_b32_dpp v173, v154 row_shr:2 row_mask:0xf bank_mask:0xf
	v_mov_b32_e32 v175, v155
	v_mov_b32_dpp v175, v155 row_shr:2 row_mask:0xf bank_mask:0xf
	s_waitcnt vmcnt(0) lgkmcnt(3)
	v_cndmask_b32_e64 v157, v156, v151, s[6:7]
	s_waitcnt lgkmcnt(2)
	v_cndmask_b32_e64 v156, v171, v150, s[6:7]
	s_waitcnt lgkmcnt(1)
	v_cndmask_b32_e64 v150, v173, v150, s[10:11]
	s_waitcnt lgkmcnt(0)
	v_cndmask_b32_e64 v151, v175, v151, s[10:11]
	v_cndmask_b32_e64 v147, v151, v147, s[6:7]
	v_cndmask_b32_e64 v146, v150, v146, s[6:7]
	v_pk_fma_f32 v[146:147], v[130:131], v[146:147], v[142:143]
	v_mov_b32_e32 v151, v176
	v_pk_fma_f32 v[146:147], v[134:135], v[156:157], v[146:147]
	s_nop 0
	v_pk_fma_f32 v[146:147], v[154:155], v[138:139], v[146:147]
	s_nop 0
	v_mul_f32_e32 v150, 0xbfb8aa3b, v146
	v_exp_f32_e32 v171, v150
	v_mov_b32_e32 v150, v176
	v_pk_mul_f32 v[156:157], v[60:61], v[150:151]
	v_mov_b32_e32 v173, v157
	s_nop 0
	v_mov_b32_dpp v173, v157 row_shr:1 row_mask:0xf bank_mask:0xf
	v_mov_b32_e32 v175, v156
	v_mov_b32_dpp v175, v156 row_shr:1 row_mask:0xf bank_mask:0xf
	v_mov_b32_e32 v177, v156
	v_mov_b32_dpp v177, v156 row_shr:2 row_mask:0xf bank_mask:0xf
	v_mov_b32_e32 v179, v157
	v_mov_b32_dpp v179, v157 row_shr:2 row_mask:0xf bank_mask:0xf
	v_add_f32_e32 v171, 1.0, v171
	s_waitcnt lgkmcnt(3)
	v_cndmask_b32_e64 v197, v173, v153, s[6:7]
	s_waitcnt lgkmcnt(2)
	v_cndmask_b32_e64 v196, v175, v152, s[6:7]
	s_waitcnt lgkmcnt(1)
	v_cndmask_b32_e64 v152, v177, v152, s[10:11]
	s_waitcnt lgkmcnt(0)
	v_cndmask_b32_e64 v153, v179, v153, s[10:11]
	v_cndmask_b32_e64 v149, v153, v149, s[6:7]
	v_cndmask_b32_e64 v148, v152, v148, s[6:7]
	v_pk_fma_f32 v[148:149], v[132:133], v[148:149], v[144:145]
	v_rcp_f32_e32 v194, v171
	v_pk_fma_f32 v[148:149], v[136:137], v[196:197], v[148:149]
	v_mul_f32_e32 v171, 0xbfb8aa3b, v147
	v_pk_fma_f32 v[148:149], v[156:157], v[140:141], v[148:149]
	v_exp_f32_e32 v171, v171
	v_mul_f32_e32 v152, 0xbfb8aa3b, v148
	v_mul_f32_e32 v153, 0xbfb8aa3b, v149
	v_exp_f32_e32 v152, v152
	v_exp_f32_e32 v153, v153
	v_add_f32_e32 v171, 1.0, v171
	v_rcp_f32_e32 v195, v171
	v_add_f32_e32 v152, 1.0, v152
	v_add_f32_e32 v153, 1.0, v153
	v_rcp_f32_e32 v152, v152
	v_rcp_f32_e32 v153, v153
	v_pk_mul_f32 v[146:147], v[146:147], v[194:195]
	v_pk_mul_f32 v[194:195], v[26:27], v[150:151]
	v_pk_mul_f32 v[150:151], v[28:29], v[150:151]
	v_pk_mul_f32 v[148:149], v[148:149], v[152:153]
	v_pk_mul_f32 v[146:147], v[194:195], v[146:147]
	v_pk_mul_f32 v[148:149], v[150:151], v[148:149]
	v_cvt_pk_bf16_f32 v146, v146, v147
	v_cvt_pk_bf16_f32 v147, v148, v149
	global_store_dwordx2 v[222:223], v[146:147], off offset:8
	s_and_saveexec_b64 s[88:89], s[8:9]
	s_cbranch_execz .LBB0_974
	v_mov_b64_e32 v[146:147], s[66:67]
	v_mad_i64_i32 v[146:147], s[20:21], v243, s48, v[146:147]
	v_lshl_add_u64 v[146:147], v[168:169], 2, v[146:147]
	global_store_dwordx4 v[146:147], v[154:157], off offset:16

; __device__ __forceinline__ unsigned cvt_pk_bf16(float lo, float hi) { f32x2_t v = {lo, hi}; bf16x2_t b = __builtin_convertvector(v, bf16x2_t); return __builtin_bit_cast(unsigned, b); }
; __device__ __forceinline__ float sigm(float x) { return __builtin_amdgcn_rcpf(1.0f + __builtin_amdgcn_exp2f(-x * LOG2E)); }
;     __device__ __forceinline__ void operator()(const f32x4 (&acc)[2][2][4][2], const Unit& u, int wr, int wc, int fr, int fq) const {
;     ...
;                         const int row = row0 + ai * HALF + m * 16, rl = row - MPR, bs = rl >> 2, t = rl & 3;
;                         const f32x4 a = acc[ai][0][m][n] * rs[ai][m], uu = acc[ai][1][m][n] * rs[ai][m]; f32x4 gg, s0 = {0.f, 0.f, 0.f, 0.f}, s1 = {0.f, 0.f, 0.f, 0.f};
;                         const float* sc = sconv + (size_t)bs * 2 * 2816 + colt + 4 * n;
;                         if (t == 0) s0 = *(const f32x4*)sc;
;                         if (t <= 1) s1 = *(const f32x4*)(sc + 2816);
; #pragma unroll
;                         for (int j = 0; j < 4; ++j) {
;                             const float up1 = __shfl_up(a[j], 1, 16), up2 = __shfl_up(a[j], 2, 16);
;                             const float p1 = t == 0 ? s1[j] : up1, p2 = t == 0 ? s0[j] : (t == 1 ? s1[j] : up2);
;                             const float c = bb[j] + w0[j] * p2 + w1[j] * p1 + w2[j] * a[j];
;                             gg[j] = c * sigm(c) * uu[j];
;                         }
;                         *(u32x2*)(G + (size_t)row * 2816 + colt + 4 * n) = (u32x2){cvt_pk_bf16(gg[0], gg[1]), cvt_pk_bf16(gg[2], gg[3])};
;                         if (t >= 2) *(f32x4*)(ocs + (size_t)(bs * 2 + t - 2) * 2816 + colt + 4 * n) = a;
.LBB0_978:
	s_or_b64 exec, exec, s[88:89]
	v_mov_b32_e32 v175, v174
	v_pk_mul_f32 v[154:155], v[50:51], v[174:175]
	v_mov_b32_e32 v156, v155
	s_nop 0
	v_mov_b32_dpp v156, v155 row_shr:1 row_mask:0xf bank_mask:0xf
	v_mov_b32_e32 v171, v154
	v_mov_b32_dpp v171, v154 row_shr:1 row_mask:0xf bank_mask:0xf
	v_mov_b32_e32 v173, v154
	v_mov_b32_dpp v173, v154 row_shr:2 row_mask:0xf bank_mask:0xf
	v_mov_b32_e32 v175, v155
	v_mov_b32_dpp v175, v155 row_shr:2 row_mask:0xf bank_mask:0xf
	s_waitcnt vmcnt(0) lgkmcnt(3)
	v_cndmask_b32_e64 v157, v156, v151, s[6:7]
	s_waitcnt lgkmcnt(2)
	v_cndmask_b32_e64 v156, v171, v150, s[6:7]
	s_waitcnt lgkmcnt(1)
	v_cndmask_b32_e64 v150, v173, v150, s[10:11]
	s_waitcnt lgkmcnt(0)
	v_cndmask_b32_e64 v151, v175, v151, s[10:11]
	v_cndmask_b32_e64 v147, v151, v147, s[6:7]
	v_cndmask_b32_e64 v146, v150, v146, s[6:7]
	v_pk_fma_f32 v[146:147], v[130:131], v[146:147], v[142:143]
	v_mov_b32_e32 v151, v174
	v_pk_fma_f32 v[146:147], v[134:135], v[156:157], v[146:147]
	s_nop 0
	v_pk_fma_f32 v[146:147], v[154:155], v[138:139], v[146:147]
	s_nop 0
	v_mul_f32_e32 v150, 0xbfb8aa3b, v146
	v_exp_f32_e32 v171, v150
	v_mov_b32_e32 v150, v174
	v_pk_mul_f32 v[156:157], v[52:53], v[150:151]
	v_mov_b32_e32 v173, v157
	s_nop 0
	v_mov_b32_dpp v173, v157 row_shr:1 row_mask:0xf bank_mask:0xf
	v_mov_b32_e32 v175, v156
	v_mov_b32_dpp v175, v156 row_shr:1 row_mask:0xf bank_mask:0xf
	v_mov_b32_e32 v177, v156
	v_mov_b32_dpp v177, v156 row_shr:2 row_mask:0xf bank_mask:0xf
	v_mov_b32_e32 v179, v157
	v_mov_b32_dpp v179, v157 row_shr:2 row_mask:0xf bank_mask:0xf
	v_add_f32_e32 v171, 1.0, v171
	s_waitcnt lgkmcnt(3)
	v_cndmask_b32_e64 v197, v173, v153, s[6:7]
	s_waitcnt lgkmcnt(2)
	v_cndmask_b32_e64 v196, v175, v152, s[6:7]
	s_waitcnt lgkmcnt(1)
	v_cndmask_b32_e64 v152, v177, v152, s[10:11]
	s_waitcnt lgkmcnt(0)
	v_cndmask_b32_e64 v153, v179, v153, s[10:11]
	v_cndmask_b32_e64 v149, v153, v149, s[6:7]
	v_cndmask_b32_e64 v148, v152, v148, s[6:7]
	v_pk_fma_f32 v[148:149], v[132:133], v[148:149], v[144:145]
	v_rcp_f32_e32 v194, v171
	v_pk_fma_f32 v[148:149], v[136:137], v[196:197], v[148:149]
	v_mul_f32_e32 v171, 0xbfb8aa3b, v147
	v_pk_fma_f32 v[148:149], v[156:157], v[140:141], v[148:149]
	v_exp_f32_e32 v171, v171
	v_mul_f32_e32 v152, 0xbfb8aa3b, v148
	v_mul_f32_e32 v153, 0xbfb8aa3b, v149
	v_exp_f32_e32 v152, v152
	v_exp_f32_e32 v153, v153
	v_add_f32_e32 v171, 1.0, v171
	v_rcp_f32_e32 v195, v171
	v_add_f32_e32 v152, 1.0, v152
	v_add_f32_e32 v153, 1.0, v153
	v_rcp_f32_e32 v152, v152
	v_rcp_f32_e32 v153, v153
	v_pk_mul_f32 v[146:147], v[146:147], v[194:195]
	v_pk_mul_f32 v[194:195], v[18:19], v[150:151]
	v_pk_mul_f32 v[150:151], v[20:21], v[150:151]
	v_pk_mul_f32 v[148:149], v[148:149], v[152:153]
	v_pk_mul_f32 v[146:147], v[194:195], v[146:147]
	v_pk_mul_f32 v[148:149], v[150:151], v[148:149]
	v_cvt_pk_bf16_f32 v146, v146, v147
	v_cvt_pk_bf16_f32 v147, v148, v149
	global_store_dwordx2 v[224:225], v[146:147], off offset:8
	s_and_saveexec_b64 s[88:89], s[8:9]
	s_cbranch_execz .LBB0_980
	v_mov_b64_e32 v[146:147], s[66:67]
	v_mad_i64_i32 v[146:147], s[20:21], v244, s48, v[146:147]
	v_lshl_add_u64 v[146:147], v[168:169], 2, v[146:147]
	global_store_dwordx4 v[146:147], v[154:157], off offset:16

; __device__ __forceinline__ unsigned cvt_pk_bf16(float lo, float hi) { f32x2_t v = {lo, hi}; bf16x2_t b = __builtin_convertvector(v, bf16x2_t); return __builtin_bit_cast(unsigned, b); }
; __device__ __forceinline__ float sigm(float x) { return __builtin_amdgcn_rcpf(1.0f + __builtin_amdgcn_exp2f(-x * LOG2E)); }
;     __device__ __forceinline__ void operator()(const f32x4 (&acc)[2][2][4][2], const Unit& u, int wr, int wc, int fr, int fq) const {
;     ...
;                         const int row = row0 + ai * HALF + m * 16, rl = row - MPR, bs = rl >> 2, t = rl & 3;
;                         const f32x4 a = acc[ai][0][m][n] * rs[ai][m], uu = acc[ai][1][m][n] * rs[ai][m]; f32x4 gg, s0 = {0.f, 0.f, 0.f, 0.f}, s1 = {0.f, 0.f, 0.f, 0.f};
;                         const float* sc = sconv + (size_t)bs * 2 * 2816 + colt + 4 * n;
;                         if (t == 0) s0 = *(const f32x4*)sc;
;                         if (t <= 1) s1 = *(const f32x4*)(sc + 2816);
; #pragma unroll
;                         for (int j = 0; j < 4; ++j) {
;                             const float up1 = __shfl_up(a[j], 1, 16), up2 = __shfl_up(a[j], 2, 16);
;                             const float p1 = t == 0 ? s1[j] : up1, p2 = t == 0 ? s0[j] : (t == 1 ? s1[j] : up2);
;                             const float c = bb[j] + w0[j] * p2 + w1[j] * p1 + w2[j] * a[j];
;                             gg[j] = c * sigm(c) * uu[j];
;                         }
;                         *(u32x2*)(G + (size_t)row * 2816 + colt + 4 * n) = (u32x2){cvt_pk_bf16(gg[0], gg[1]), cvt_pk_bf16(gg[2], gg[3])};
;                         if (t >= 2) *(f32x4*)(ocs + (size_t)(bs * 2 + t - 2) * 2816 + colt + 4 * n) = a;
.LBB0_984:
	s_or_b64 exec, exec, s[88:89]
	v_mov_b32_e32 v173, v172
	v_pk_mul_f32 v[154:155], v[42:43], v[172:173]
	v_mov_b32_e32 v156, v155
	s_nop 0
	v_mov_b32_dpp v156, v155 row_shr:1 row_mask:0xf bank_mask:0xf
	v_mov_b32_e32 v171, v154
	v_mov_b32_dpp v171, v154 row_shr:1 row_mask:0xf bank_mask:0xf
	v_mov_b32_e32 v173, v154
	v_mov_b32_dpp v173, v154 row_shr:2 row_mask:0xf bank_mask:0xf
	v_mov_b32_e32 v175, v155
	v_mov_b32_dpp v175, v155 row_shr:2 row_mask:0xf bank_mask:0xf
	s_waitcnt vmcnt(0) lgkmcnt(3)
	v_cndmask_b32_e64 v157, v156, v151, s[6:7]
	s_waitcnt lgkmcnt(2)
	v_cndmask_b32_e64 v156, v171, v150, s[6:7]
	s_waitcnt lgkmcnt(1)
	v_cndmask_b32_e64 v150, v173, v150, s[10:11]
	s_waitcnt lgkmcnt(0)
	v_cndmask_b32_e64 v151, v175, v151, s[10:11]
	v_cndmask_b32_e64 v147, v151, v147, s[6:7]
	v_cndmask_b32_e64 v146, v150, v146, s[6:7]
	v_pk_fma_f32 v[146:147], v[130:131], v[146:147], v[142:143]
	v_mov_b32_e32 v151, v172
	v_pk_fma_f32 v[146:147], v[134:135], v[156:157], v[146:147]
	s_nop 0
	v_pk_fma_f32 v[146:147], v[154:155], v[138:139], v[146:147]
	s_nop 0
	v_mul_f32_e32 v150, 0xbfb8aa3b, v146
	v_exp_f32_e32 v171, v150
	v_mov_b32_e32 v150, v172
	v_pk_mul_f32 v[156:157], v[44:45], v[150:151]
	v_mov_b32_e32 v173, v157
	s_nop 0
	v_mov_b32_dpp v173, v157 row_shr:1 row_mask:0xf bank_mask:0xf
	v_mov_b32_e32 v175, v156
	v_mov_b32_dpp v175, v156 row_shr:1 row_mask:0xf bank_mask:0xf
	v_mov_b32_e32 v177, v156
	v_mov_b32_dpp v177, v156 row_shr:2 row_mask:0xf bank_mask:0xf
	v_mov_b32_e32 v179, v157
	v_mov_b32_dpp v179, v157 row_shr:2 row_mask:0xf bank_mask:0xf
	v_add_f32_e32 v171, 1.0, v171
	s_waitcnt lgkmcnt(3)
	v_cndmask_b32_e64 v197, v173, v153, s[6:7]
	s_waitcnt lgkmcnt(2)
	v_cndmask_b32_e64 v196, v175, v152, s[6:7]
	s_waitcnt lgkmcnt(1)
	v_cndmask_b32_e64 v152, v177, v152, s[10:11]
	s_waitcnt lgkmcnt(0)
	v_cndmask_b32_e64 v153, v179, v153, s[10:11]
	v_cndmask_b32_e64 v149, v153, v149, s[6:7]
	v_cndmask_b32_e64 v148, v152, v148, s[6:7]
	v_pk_fma_f32 v[148:149], v[132:133], v[148:149], v[144:145]
	v_rcp_f32_e32 v194, v171
	v_pk_fma_f32 v[148:149], v[136:137], v[196:197], v[148:149]
	v_mul_f32_e32 v171, 0xbfb8aa3b, v147
	v_pk_fma_f32 v[148:149], v[156:157], v[140:141], v[148:149]
	v_exp_f32_e32 v171, v171
	v_mul_f32_e32 v152, 0xbfb8aa3b, v148
	v_mul_f32_e32 v153, 0xbfb8aa3b, v149
	v_exp_f32_e32 v152, v152
	v_exp_f32_e32 v153, v153
	v_add_f32_e32 v171, 1.0, v171
	v_rcp_f32_e32 v195, v171
	v_add_f32_e32 v152, 1.0, v152
	v_add_f32_e32 v153, 1.0, v153
	v_rcp_f32_e32 v152, v152
	v_rcp_f32_e32 v153, v153
	v_pk_mul_f32 v[146:147], v[146:147], v[194:195]
	v_pk_mul_f32 v[194:195], v[10:11], v[150:151]
	v_pk_mul_f32 v[150:151], v[12:13], v[150:151]
	v_pk_mul_f32 v[148:149], v[148:149], v[152:153]
	v_pk_mul_f32 v[146:147], v[194:195], v[146:147]
	v_pk_mul_f32 v[148:149], v[150:151], v[148:149]
	v_cvt_pk_bf16_f32 v146, v146, v147
	v_cvt_pk_bf16_f32 v147, v148, v149
	global_store_dwordx2 v[226:227], v[146:147], off offset:8
	s_and_saveexec_b64 s[88:89], s[8:9]
	s_cbranch_execz .LBB0_986
	v_mov_b64_e32 v[146:147], s[66:67]
	v_mad_i64_i32 v[146:147], s[20:21], v245, s48, v[146:147]
	v_lshl_add_u64 v[146:147], v[168:169], 2, v[146:147]
	global_store_dwordx4 v[146:147], v[154:157], off offset:16

; __device__ __forceinline__ unsigned cvt_pk_bf16(float lo, float hi) { f32x2_t v = {lo, hi}; bf16x2_t b = __builtin_convertvector(v, bf16x2_t); return __builtin_bit_cast(unsigned, b); }
; __device__ __forceinline__ float sigm(float x) { return __builtin_amdgcn_rcpf(1.0f + __builtin_amdgcn_exp2f(-x * LOG2E)); }
;     __device__ __forceinline__ void operator()(const f32x4 (&acc)[2][2][4][2], const Unit& u, int wr, int wc, int fr, int fq) const {
;     ...
;                         const int row = row0 + ai * HALF + m * 16, rl = row - MPR, bs = rl >> 2, t = rl & 3;
;                         const f32x4 a = acc[ai][0][m][n] * rs[ai][m], uu = acc[ai][1][m][n] * rs[ai][m]; f32x4 gg, s0 = {0.f, 0.f, 0.f, 0.f}, s1 = {0.f, 0.f, 0.f, 0.f};
;                         const float* sc = sconv + (size_t)bs * 2 * 2816 + colt + 4 * n;
;                         if (t == 0) s0 = *(const f32x4*)sc;
;                         if (t <= 1) s1 = *(const f32x4*)(sc + 2816);
; #pragma unroll
;                         for (int j = 0; j < 4; ++j) {
;                             const float up1 = __shfl_up(a[j], 1, 16), up2 = __shfl_up(a[j], 2, 16);
;                             const float p1 = t == 0 ? s1[j] : up1, p2 = t == 0 ? s0[j] : (t == 1 ? s1[j] : up2);
;                             const float c = bb[j] + w0[j] * p2 + w1[j] * p1 + w2[j] * a[j];
;                             gg[j] = c * sigm(c) * uu[j];
;                         }
;                         *(u32x2*)(G + (size_t)row * 2816 + colt + 4 * n) = (u32x2){cvt_pk_bf16(gg[0], gg[1]), cvt_pk_bf16(gg[2], gg[3])};
;                         if (t >= 2) *(f32x4*)(ocs + (size_t)(bs * 2 + t - 2) * 2816 + colt + 4 * n) = a;
.LBB0_990:
	s_or_b64 exec, exec, s[88:89]
	v_mov_b32_e32 v171, v170
	v_pk_mul_f32 v[146:147], v[34:35], v[170:171]
	v_mov_b32_e32 v156, v147
	s_nop 0
	v_mov_b32_dpp v156, v147 row_shr:1 row_mask:0xf bank_mask:0xf
	v_mov_b32_e32 v171, v146
	v_mov_b32_dpp v171, v146 row_shr:1 row_mask:0xf bank_mask:0xf
	v_mov_b32_e32 v173, v146
	v_mov_b32_dpp v173, v146 row_shr:2 row_mask:0xf bank_mask:0xf
	v_mov_b32_e32 v175, v147
	v_mov_b32_dpp v175, v147 row_shr:2 row_mask:0xf bank_mask:0xf
	s_waitcnt vmcnt(0) lgkmcnt(3)
	v_cndmask_b32_e64 v157, v156, v153, s[6:7]
	s_waitcnt lgkmcnt(2)
	v_cndmask_b32_e64 v156, v171, v152, s[6:7]
	s_waitcnt lgkmcnt(1)
	v_cndmask_b32_e64 v152, v173, v152, s[10:11]
	s_waitcnt lgkmcnt(0)
	v_cndmask_b32_e64 v153, v175, v153, s[10:11]
	v_cndmask_b32_e64 v149, v153, v149, s[6:7]
	v_cndmask_b32_e64 v148, v152, v148, s[6:7]
	v_pk_fma_f32 v[130:131], v[130:131], v[148:149], v[142:143]
	s_nop 0
	v_pk_fma_f32 v[130:131], v[134:135], v[156:157], v[130:131]
	v_mov_b32_e32 v135, v170
	v_pk_fma_f32 v[130:131], v[146:147], v[138:139], v[130:131]
	s_nop 0
	v_mul_f32_e32 v134, 0xbfb8aa3b, v130
	v_exp_f32_e32 v138, v134
	v_mov_b32_e32 v134, v170
	v_pk_mul_f32 v[148:149], v[36:37], v[134:135]
	v_mov_b32_e32 v142, v149
	s_nop 0
	v_mov_b32_dpp v142, v149 row_shr:1 row_mask:0xf bank_mask:0xf
	v_mov_b32_e32 v152, v148
	v_mov_b32_dpp v152, v148 row_shr:1 row_mask:0xf bank_mask:0xf
	v_mov_b32_e32 v153, v148
	v_mov_b32_dpp v153, v148 row_shr:2 row_mask:0xf bank_mask:0xf
	v_mov_b32_e32 v156, v149
	v_mov_b32_dpp v156, v149 row_shr:2 row_mask:0xf bank_mask:0xf
	v_mul_f32_e32 v139, 0xbfb8aa3b, v131
	s_waitcnt lgkmcnt(3)
	v_cndmask_b32_e64 v143, v142, v155, s[6:7]
	s_waitcnt lgkmcnt(2)
	v_cndmask_b32_e64 v142, v152, v154, s[6:7]
	s_waitcnt lgkmcnt(1)
	v_cndmask_b32_e64 v152, v153, v154, s[10:11]
	s_waitcnt lgkmcnt(0)
	v_cndmask_b32_e64 v153, v156, v155, s[10:11]
	v_cndmask_b32_e64 v151, v153, v151, s[6:7]
	v_cndmask_b32_e64 v150, v152, v150, s[6:7]
	v_pk_fma_f32 v[132:133], v[132:133], v[150:151], v[144:145]
	v_exp_f32_e32 v139, v139
	v_pk_fma_f32 v[132:133], v[136:137], v[142:143], v[132:133]
	v_add_f32_e32 v138, 1.0, v138
	v_pk_fma_f32 v[132:133], v[148:149], v[140:141], v[132:133]
	v_add_f32_e32 v139, 1.0, v139
	v_mul_f32_e32 v136, 0xbfb8aa3b, v132
	v_mul_f32_e32 v137, 0xbfb8aa3b, v133
	v_exp_f32_e32 v136, v136
	v_exp_f32_e32 v137, v137
	v_rcp_f32_e32 v138, v138
	v_rcp_f32_e32 v139, v139
	v_add_f32_e32 v136, 1.0, v136
	v_add_f32_e32 v137, 1.0, v137
	v_rcp_f32_e32 v136, v136
	v_rcp_f32_e32 v137, v137
	v_pk_mul_f32 v[130:131], v[130:131], v[138:139]
	v_pk_mul_f32 v[138:139], v[2:3], v[134:135]
	v_pk_mul_f32 v[134:135], v[4:5], v[134:135]
	v_pk_mul_f32 v[132:133], v[132:133], v[136:137]
	v_pk_mul_f32 v[130:131], v[138:139], v[130:131]
	v_pk_mul_f32 v[132:133], v[134:135], v[132:133]
	v_cvt_pk_bf16_f32 v130, v130, v131
	v_cvt_pk_bf16_f32 v131, v132, v133
	s_mov_b64 s[6:7], 0
	s_mov_b64 s[10:11], 0
	global_store_dwordx2 v[228:229], v[130:131], off offset:8
	s_and_saveexec_b64 s[12:13], s[8:9]
	s_xor_b64 s[8:9], exec, s[12:13]
	s_mov_b64 s[10:11], exec
	s_or_b64 exec, exec, s[8:9]
	s_mov_b64 s[8:9], 0xa48b000
	s_and_b64 vcc, exec, s[6:7]
	s_cbranch_vccnz .LBB0_994
	s_branch .LBB0_1018
